# thin phases: ctx-row loops (merge/outproj/norm) and s5_out A-fragment loads issued ahead with counted waits; attention DPP max + mask skip; conv dealt from the other end
# speedup vs baseline: 1.0087x; 1.0019x over previous
; __device__ __forceinline__ unsigned pk2(float lo, float hi) { const f32x2 v = {lo, hi}; return __builtin_bit_cast(unsigned, __builtin_convertvector(v, bf16x2_t)); }
; __device__ __forceinline__ void norm_ctx_rows(const PA& a, int layer, int gw, int NGW, int lane) {
;     ...
;     for (int rc = gw; rc < NCTX; rc += NGW) {
;     ...
;         u32x2* o8 = (u32x2*)(H + (size_t)(NLAT + rc) * D) + lane;
; #pragma unroll
;         for (int j = 0; j < 8; ++j) { const int col = (lane + 64 * j) * 4;
;             const f32x4 y = v[j] * *(const f32x4*)(ng + col) * (*(const f32x4*)(mv + D + col) + 1.f);
;             o8[64 * j] = (u32x2){pk2(y.x, y.y), pk2(y.z, y.w)}; }
.LBB0_170:
	s_or_b64 exec, exec, s[18:19]
	global_load_dwordx4 v[92:95], v[50:51], off
	global_load_dwordx4 v[96:99], v[52:53], off
	global_load_dwordx4 v[100:103], v[50:51], off offset:1024
	global_load_dwordx4 v[104:107], v[54:55], off
	global_load_dwordx4 v[108:111], v[50:51], off offset:2048
	global_load_dwordx4 v[112:115], v[56:57], off
	global_load_dwordx4 v[116:119], v[50:51], off offset:3072
	global_load_dwordx4 v[120:123], v[58:59], off
	global_load_dwordx4 v[124:127], v[60:61], off
	global_load_dwordx4 v[128:131], v[62:63], off
	global_load_dwordx4 v[132:135], v[64:65], off
	global_load_dwordx4 v[136:139], v[66:67], off
	global_load_dwordx4 v[140:143], v[68:69], off
	global_load_dwordx4 v[144:147], v[70:71], off
	global_load_dwordx4 v[148:151], v[72:73], off
	global_load_dwordx4 v[152:155], v[74:75], off
	s_add_i32 s4, s6, 0x8000
	s_ashr_i32 s5, s4, 31
	s_lshl_b64 s[4:5], s[4:5], 12
	s_waitcnt lgkmcnt(0)
	v_lshl_add_u64 v[76:77], v[32:33], 0, s[4:5]
	s_add_i32 s6, s6, s8
	s_add_u32 s20, s20, s10
	s_addc_u32 s21, s21, s11
	s_add_u32 s14, s14, s16
	s_addc_u32 s15, s15, s17
	s_add_u32 s12, s12, s16
	s_addc_u32 s13, s13, s17
	s_cmpk_lt_i32 s6, 0x400
	s_waitcnt vmcnt(15)
	v_pk_mul_f32 v[80:81], v[2:3], v[94:95]
	v_pk_mul_f32 v[78:79], v[0:1], v[92:93]
	s_waitcnt vmcnt(14)
	v_pk_add_f32 v[2:3], v[98:99], 1.0 op_sel_hi:[1,0]
	v_pk_add_f32 v[0:1], v[96:97], 1.0 op_sel_hi:[1,0]
	v_pk_mul_f32 v[2:3], v[80:81], v[2:3]
	v_pk_mul_f32 v[0:1], v[78:79], v[0:1]
	s_nop 0
	v_cvt_pk_bf16_f32 v0, v0, v1
	v_cvt_pk_bf16_f32 v1, v2, v3
	global_store_dwordx2 v[76:77], v[0:1], off
	s_waitcnt vmcnt(14)
	v_pk_mul_f32 v[6:7], v[6:7], v[102:103]
	v_pk_mul_f32 v[4:5], v[4:5], v[100:101]
	s_waitcnt vmcnt(13)
	v_pk_add_f32 v[2:3], v[106:107], 1.0 op_sel_hi:[1,0]
	v_pk_add_f32 v[0:1], v[104:105], 1.0 op_sel_hi:[1,0]
	v_pk_mul_f32 v[2:3], v[6:7], v[2:3]
	v_pk_mul_f32 v[0:1], v[4:5], v[0:1]
	s_nop 0
	v_cvt_pk_bf16_f32 v0, v0, v1
	v_cvt_pk_bf16_f32 v1, v2, v3
	global_store_dwordx2 v[76:77], v[0:1], off offset:512
	s_waitcnt vmcnt(13)
	v_pk_mul_f32 v[4:5], v[10:11], v[110:111]
	v_pk_mul_f32 v[6:7], v[8:9], v[108:109]
	s_waitcnt vmcnt(12)
	v_pk_add_f32 v[2:3], v[114:115], 1.0 op_sel_hi:[1,0]
	v_pk_add_f32 v[0:1], v[112:113], 1.0 op_sel_hi:[1,0]
	v_pk_mul_f32 v[2:3], v[4:5], v[2:3]
	v_pk_mul_f32 v[0:1], v[6:7], v[0:1]
	s_nop 0
	v_cvt_pk_bf16_f32 v0, v0, v1
	v_cvt_pk_bf16_f32 v1, v2, v3
	global_store_dwordx2 v[76:77], v[0:1], off offset:1024
	s_waitcnt vmcnt(12)
	v_pk_mul_f32 v[4:5], v[14:15], v[118:119]
	v_pk_mul_f32 v[6:7], v[12:13], v[116:117]
	s_waitcnt vmcnt(11)
	v_pk_add_f32 v[2:3], v[122:123], 1.0 op_sel_hi:[1,0]
	v_pk_add_f32 v[0:1], v[120:121], 1.0 op_sel_hi:[1,0]
	v_pk_mul_f32 v[2:3], v[4:5], v[2:3]
	v_pk_mul_f32 v[0:1], v[6:7], v[0:1]
	s_nop 0
	v_cvt_pk_bf16_f32 v0, v0, v1
	v_cvt_pk_bf16_f32 v1, v2, v3
	global_store_dwordx2 v[76:77], v[0:1], off offset:1536
	s_waitcnt vmcnt(11)
	v_pk_mul_f32 v[4:5], v[18:19], v[126:127]
	v_pk_mul_f32 v[6:7], v[16:17], v[124:125]
	s_waitcnt vmcnt(10)
	v_pk_add_f32 v[2:3], v[130:131], 1.0 op_sel_hi:[1,0]
	v_pk_add_f32 v[0:1], v[128:129], 1.0 op_sel_hi:[1,0]
	v_pk_mul_f32 v[2:3], v[4:5], v[2:3]
	v_pk_mul_f32 v[0:1], v[6:7], v[0:1]
	s_nop 0
	v_cvt_pk_bf16_f32 v0, v0, v1
	v_cvt_pk_bf16_f32 v1, v2, v3
	global_store_dwordx2 v[76:77], v[0:1], off offset:2048
	s_waitcnt vmcnt(10)
	v_pk_mul_f32 v[4:5], v[22:23], v[134:135]
	v_pk_mul_f32 v[6:7], v[20:21], v[132:133]
	s_waitcnt vmcnt(9)
	v_pk_add_f32 v[2:3], v[138:139], 1.0 op_sel_hi:[1,0]
	v_pk_add_f32 v[0:1], v[136:137], 1.0 op_sel_hi:[1,0]
	v_pk_mul_f32 v[2:3], v[4:5], v[2:3]
	v_pk_mul_f32 v[0:1], v[6:7], v[0:1]
	s_nop 0
	v_cvt_pk_bf16_f32 v0, v0, v1
	v_cvt_pk_bf16_f32 v1, v2, v3
	global_store_dwordx2 v[76:77], v[0:1], off offset:2560
	s_waitcnt vmcnt(9)
	v_pk_mul_f32 v[4:5], v[26:27], v[142:143]
	v_pk_mul_f32 v[6:7], v[24:25], v[140:141]
	s_waitcnt vmcnt(8)
	v_pk_add_f32 v[2:3], v[146:147], 1.0 op_sel_hi:[1,0]
	v_pk_add_f32 v[0:1], v[144:145], 1.0 op_sel_hi:[1,0]
	v_pk_mul_f32 v[2:3], v[4:5], v[2:3]
	v_pk_mul_f32 v[0:1], v[6:7], v[0:1]
	s_nop 0
	v_cvt_pk_bf16_f32 v0, v0, v1
	v_cvt_pk_bf16_f32 v1, v2, v3
	global_store_dwordx2 v[76:77], v[0:1], off offset:3072
	s_waitcnt vmcnt(8)
	v_pk_mul_f32 v[4:5], v[30:31], v[150:151]
	v_pk_mul_f32 v[6:7], v[28:29], v[148:149]
	s_waitcnt vmcnt(7)
	v_pk_add_f32 v[2:3], v[154:155], 1.0 op_sel_hi:[1,0]
	v_pk_add_f32 v[0:1], v[152:153], 1.0 op_sel_hi:[1,0]
	v_pk_mul_f32 v[2:3], v[4:5], v[2:3]
	v_pk_mul_f32 v[0:1], v[6:7], v[0:1]
	s_nop 0
	v_cvt_pk_bf16_f32 v0, v0, v1
	v_cvt_pk_bf16_f32 v1, v2, v3
	global_store_dwordx2 v[76:77], v[0:1], off offset:3584
	s_cbranch_scc0 .LBB0_173
;     __device__ __forceinline__ unsigned char* ws() const { return (unsigned char*)(__attribute__((address_space(1))) unsigned char*)get(35); }
; __device__ __forceinline__ void norm_ctx_rows(const PA& a, int layer, int gw, int NGW, int lane) {
;     ...
;     for (int rc = gw; rc < NCTX; rc += NGW) {
;         f32x4* xr = (f32x4*)(a.ws() + WS_XC + (size_t)rc * D * 4) + lane; f32x4 v[8]; float ss = 0.f;
; #pragma unroll
;         for (int j = 0; j < 8; ++j) { const int col = (lane + 64 * j) * 4; const float* pp = part + (size_t)rc * D + col;
;             const f32x4 p = ((*(const f32x4*)pp + *(const f32x4*)(pp + (size_t)NCTX * D)) + *(const f32x4*)(pp + (size_t)2 * NCTX * D)) + *(const f32x4*)(pp + (size_t)3 * NCTX * D);
;             v[j] = xr[64 * j] + *(const f32x4*)(g2 + col) * p; xr[64 * j] = v[j];
;             ss += (v[j].x * v[j].x + v[j].y * v[j].y) + (v[j].z * v[j].z + v[j].w * v[j].w); }
.LBB0_171:
	v_mov_b32 v0, 0
	v_lshl_add_u64 v[18:19], s[14:15], 0, v[208:209]
	v_add_u32_e32 v0, s79, v0
	ds_read_b32 v1, v0 offset:280
	ds_read_b32 v0, v0 offset:284
	v_add_co_u32_e32 v12, vcc, 0x56800000, v18
	s_waitcnt lgkmcnt(1)
	v_readfirstlane_b32 s4, v1
	v_addc_co_u32_e32 v13, vcc, 0, v19, vcc
	global_load_dwordx4 v[92:95], v[12:13], off
	s_waitcnt lgkmcnt(0)
	v_readfirstlane_b32 s5, v0
	v_add_co_u32_e32 v14, vcc, 0x57000000, v18
	s_nop 0
	v_lshl_add_u64 v[0:1], s[4:5], 0, v[208:209]
	v_addc_co_u32_e32 v15, vcc, 0, v19, vcc
	global_load_dwordx4 v[96:99], v[14:15], off
	v_lshl_add_u64 v[16:17], v[0:1], 0, s[12:13]
	v_add_co_u32_e32 v22, vcc, 0x57800000, v18
	s_mov_b32 s4, 0xbe01000
	s_nop 0
	v_addc_co_u32_e32 v23, vcc, 0, v19, vcc
	global_load_dwordx4 v[100:103], v[22:23], off
	v_add_co_u32_e32 v24, vcc, 0x58000000, v18
	s_waitcnt vmcnt(1)
	v_pk_add_f32 v[6:7], v[94:95], v[98:99]
	v_pk_add_f32 v[4:5], v[92:93], v[96:97]
	v_addc_co_u32_e32 v25, vcc, 0, v19, vcc
	global_load_dwordx4 v[104:107], v[24:25], off
	v_add_co_u32_e32 v20, vcc, 0xbe00000, v16
	s_waitcnt vmcnt(1)
	v_pk_add_f32 v[6:7], v[6:7], v[102:103]
	v_pk_add_f32 v[4:5], v[4:5], v[100:101]
	v_addc_co_u32_e32 v21, vcc, 0, v17, vcc
	global_load_dwordx4 v[108:111], v[20:21], off
	global_load_dwordx4 v[112:115], v[34:35], off
	global_load_dwordx4 v[116:119], v[12:13], off offset:1024
	global_load_dwordx4 v[120:123], v[14:15], off offset:1024
	global_load_dwordx4 v[124:127], v[22:23], off offset:1024
	global_load_dwordx4 v[128:131], v[24:25], off offset:1024
	global_load_dwordx4 v[132:135], v[20:21], off offset:1024
	global_load_dwordx4 v[136:139], v[36:37], off
	global_load_dwordx4 v[140:143], v[12:13], off offset:2048
	global_load_dwordx4 v[144:147], v[14:15], off offset:2048
	global_load_dwordx4 v[148:151], v[22:23], off offset:2048
	global_load_dwordx4 v[152:155], v[24:25], off offset:2048
	global_load_dwordx4 v[156:159], v[20:21], off offset:2048
	global_load_dwordx4 v[160:163], v[38:39], off
	global_load_dwordx4 v[164:167], v[12:13], off offset:3072
	global_load_dwordx4 v[168:171], v[14:15], off offset:3072
	global_load_dwordx4 v[172:175], v[22:23], off offset:3072
	global_load_dwordx4 v[176:179], v[24:25], off offset:3072
	global_load_dwordx4 v[180:183], v[20:21], off offset:3072
	global_load_dwordx4 v[184:187], v[40:41], off
	s_waitcnt vmcnt(20)
	v_pk_add_f32 v[8:9], v[6:7], v[106:107]
	v_pk_add_f32 v[10:11], v[4:5], v[104:105]
	s_waitcnt vmcnt(18)
	v_pk_fma_f32 v[2:3], v[8:9], v[114:115], v[110:111]
	v_pk_fma_f32 v[0:1], v[10:11], v[112:113], v[108:109]
	v_mul_f32_e32 v5, v3, v3
	v_mul_f32_e32 v4, v1, v1
	global_store_dwordx4 v[20:21], v[0:3], off
	v_fmac_f32_e32 v4, v0, v0
	v_fmac_f32_e32 v5, v2, v2
	v_add_f32_e32 v30, v4, v5
	s_waitcnt vmcnt(17)
	v_pk_add_f32 v[10:11], v[118:119], v[122:123]
	v_pk_add_f32 v[8:9], v[116:117], v[120:121]
	s_waitcnt vmcnt(16)
	v_pk_add_f32 v[10:11], v[10:11], v[126:127]
	v_pk_add_f32 v[8:9], v[8:9], v[124:125]
	s_waitcnt vmcnt(15)
	v_pk_add_f32 v[26:27], v[10:11], v[130:131]
	v_pk_add_f32 v[28:29], v[8:9], v[128:129]
	s_waitcnt vmcnt(13)
	v_pk_fma_f32 v[6:7], v[26:27], v[138:139], v[134:135]
	v_pk_fma_f32 v[4:5], v[28:29], v[136:137], v[132:133]
	v_mul_f32_e32 v9, v7, v7
	v_mul_f32_e32 v8, v5, v5
	v_fmac_f32_e32 v8, v4, v4
	v_fmac_f32_e32 v9, v6, v6
	global_store_dwordx4 v[20:21], v[4:7], off offset:1024
	v_add_f32_e32 v8, v8, v9
	v_add_f32_e32 v78, v30, v8
	s_waitcnt vmcnt(12)
	v_pk_add_f32 v[28:29], v[142:143], v[146:147]
	v_pk_add_f32 v[26:27], v[140:141], v[144:145]
	s_waitcnt vmcnt(11)
	v_pk_add_f32 v[28:29], v[28:29], v[150:151]
	v_pk_add_f32 v[26:27], v[26:27], v[148:149]
	s_waitcnt vmcnt(10)
	v_pk_add_f32 v[30:31], v[28:29], v[154:155]
	v_pk_add_f32 v[76:77], v[26:27], v[152:153]
	s_waitcnt vmcnt(8)
	v_pk_fma_f32 v[10:11], v[30:31], v[162:163], v[158:159]
	v_pk_fma_f32 v[8:9], v[76:77], v[160:161], v[156:157]
	v_mul_f32_e32 v27, v11, v11
	v_mul_f32_e32 v26, v9, v9
	v_fmac_f32_e32 v26, v8, v8
	v_fmac_f32_e32 v27, v10, v10
	global_store_dwordx4 v[20:21], v[8:11], off offset:2048
	v_add_f32_e32 v26, v26, v27
	v_add_f32_e32 v30, v78, v26
	s_nop 0
	s_waitcnt vmcnt(7)
	v_pk_add_f32 v[28:29], v[166:167], v[170:171]
	v_pk_add_f32 v[26:27], v[164:165], v[168:169]
	s_waitcnt vmcnt(6)
	v_pk_add_f32 v[22:23], v[28:29], v[174:175]
	v_pk_add_f32 v[26:27], v[26:27], v[172:173]
	s_waitcnt vmcnt(5)
	v_pk_add_f32 v[28:29], v[22:23], v[178:179]
	v_pk_add_f32 v[26:27], v[26:27], v[176:177]
	s_waitcnt vmcnt(3)
	v_pk_fma_f32 v[14:15], v[28:29], v[186:187], v[182:183]
	v_pk_fma_f32 v[12:13], v[26:27], v[184:185], v[180:181]
	global_store_dwordx4 v[20:21], v[12:15], off offset:3072
	v_mul_f32_e32 v20, v13, v13
	v_mul_f32_e32 v21, v15, v15
	v_fmac_f32_e32 v20, v12, v12
	v_fmac_f32_e32 v21, v14, v14
	v_add_co_u32_e32 v28, vcc, s67, v18
	v_add_f32_e32 v20, v20, v21
	s_nop 0
	v_addc_co_u32_e32 v29, vcc, 0, v19, vcc
	global_load_dwordx4 v[188:191], v[28:29], off
	v_add_f32_e32 v82, v30, v20
	v_add_co_u32_e32 v30, vcc, s68, v18
	s_nop 0
	v_addc_co_u32_e32 v31, vcc, 0, v19, vcc
	global_load_dwordx4 v[192:195], v[30:31], off
	v_add_co_u32_e32 v78, vcc, s69, v18
	s_waitcnt vmcnt(0)
	v_pk_add_f32 v[26:27], v[190:191], v[194:195]
	v_addc_co_u32_e32 v79, vcc, 0, v19, vcc
	global_load_dwordx4 v[196:199], v[78:79], off
	v_pk_add_f32 v[24:25], v[188:189], v[192:193]
	v_add_co_u32_e32 v80, vcc, s70, v18
	s_waitcnt vmcnt(0)
; __device__ __forceinline__ float wave_sum(float v) { v += shx<1>(v); v += shx<2>(v); v += shx<4>(v); v += shx<8>(v); v += shx<16>(v); v += shx<32>(v); return v; }
;     __device__ __forceinline__ unsigned char* ws() const { return (unsigned char*)(__attribute__((address_space(1))) unsigned char*)get(35); }
; __device__ __forceinline__ void norm_ctx_rows(const PA& a, int layer, int gw, int NGW, int lane) {
;     ...
;         f32x4* xr = (f32x4*)(a.ws() + WS_XC + (size_t)rc * D * 4) + lane; f32x4 v[8]; float ss = 0.f;
; #pragma unroll
;         for (int j = 0; j < 8; ++j) { const int col = (lane + 64 * j) * 4; const float* pp = part + (size_t)rc * D + col;
;             const f32x4 p = ((*(const f32x4*)pp + *(const f32x4*)(pp + (size_t)NCTX * D)) + *(const f32x4*)(pp + (size_t)2 * NCTX * D)) + *(const f32x4*)(pp + (size_t)3 * NCTX * D);
;             v[j] = xr[64 * j] + *(const f32x4*)(g2 + col) * p; xr[64 * j] = v[j];
;             ss += (v[j].x * v[j].x + v[j].y * v[j].y) + (v[j].z * v[j].z + v[j].w * v[j].w); }
;         const float sm = wave_sum(ss); if (lane == 0) ((float*)(a.ws() + WS_RS1))[NLAT + rc] = 1.f / sqrtf(sm * (1.f / D) + EPS);
	v_pk_add_f32 v[24:25], v[24:25], v[196:197]
	v_addc_co_u32_e32 v81, vcc, 0, v19, vcc
	global_load_dwordx4 v[200:203], v[80:81], off
	v_add_co_u32_e32 v76, vcc, s4, v16
	v_pk_add_f32 v[22:23], v[26:27], v[198:199]
	s_nop 0
	v_addc_co_u32_e32 v77, vcc, 0, v17, vcc
	global_load_dwordx4 v[204:207], v[76:77], off
	global_load_dwordx4 v[210:213], v[42:43], off
	global_load_dwordx4 v[214:217], v[28:29], off offset:1024
	global_load_dwordx4 v[218:221], v[30:31], off offset:1024
	global_load_dwordx4 v[222:225], v[78:79], off offset:1024
	global_load_dwordx4 v[226:229], v[80:81], off offset:1024
	global_load_dwordx4 v[230:233], v[76:77], off offset:1024
	global_load_dwordx4 v[234:237], v[44:45], off
	global_load_dwordx4 v[238:241], v[28:29], off offset:2048
	global_load_dwordx4 v[242:245], v[30:31], off offset:2048
	global_load_dwordx4 v[246:249], v[78:79], off offset:2048
	global_load_dwordx4 v[92:95], v[80:81], off offset:2048
	global_load_dwordx4 v[96:99], v[76:77], off offset:2048
	global_load_dwordx4 v[100:103], v[46:47], off
	global_load_dwordx4 v[104:107], v[28:29], off offset:3072
	global_load_dwordx4 v[108:111], v[30:31], off offset:3072
	global_load_dwordx4 v[112:115], v[78:79], off offset:3072
	global_load_dwordx4 v[116:119], v[80:81], off offset:3072
	global_load_dwordx4 v[120:123], v[76:77], off offset:3072
	global_load_dwordx4 v[124:127], v[48:49], off
	s_waitcnt vmcnt(20)
	v_pk_add_f32 v[26:27], v[22:23], v[202:203]
	v_pk_add_f32 v[24:25], v[24:25], v[200:201]
	s_waitcnt vmcnt(18)
	v_pk_fma_f32 v[18:19], v[26:27], v[212:213], v[206:207]
	v_pk_fma_f32 v[16:17], v[24:25], v[210:211], v[204:205]
	v_mul_f32_e32 v21, v19, v19
	v_mul_f32_e32 v20, v17, v17
	v_fmac_f32_e32 v20, v16, v16
	v_fmac_f32_e32 v21, v18, v18
	global_store_dwordx4 v[76:77], v[16:19], off
	v_add_f32_e32 v20, v20, v21
	v_add_f32_e32 v86, v82, v20
	s_waitcnt vmcnt(17)
	v_pk_add_f32 v[26:27], v[216:217], v[220:221]
	v_pk_add_f32 v[24:25], v[214:215], v[218:219]
	s_waitcnt vmcnt(16)
	v_pk_add_f32 v[26:27], v[26:27], v[224:225]
	v_pk_add_f32 v[24:25], v[24:25], v[222:223]
	s_waitcnt vmcnt(15)
	v_pk_add_f32 v[82:83], v[26:27], v[228:229]
	v_pk_add_f32 v[84:85], v[24:25], v[226:227]
	s_waitcnt vmcnt(13)
	v_pk_fma_f32 v[22:23], v[82:83], v[236:237], v[232:233]
	v_pk_fma_f32 v[20:21], v[84:85], v[234:235], v[230:231]
	v_mul_f32_e32 v25, v23, v23
	v_mul_f32_e32 v24, v21, v21
	v_fmac_f32_e32 v24, v20, v20
	v_fmac_f32_e32 v25, v22, v22
	global_store_dwordx4 v[76:77], v[20:23], off offset:1024
	v_add_f32_e32 v24, v24, v25
	v_add_f32_e32 v90, v86, v24
	s_waitcnt vmcnt(12)
	v_pk_add_f32 v[84:85], v[240:241], v[244:245]
	v_pk_add_f32 v[82:83], v[238:239], v[242:243]
	s_waitcnt vmcnt(11)
	v_pk_add_f32 v[84:85], v[84:85], v[248:249]
	v_pk_add_f32 v[82:83], v[82:83], v[246:247]
	s_waitcnt vmcnt(10)
	v_pk_add_f32 v[86:87], v[84:85], v[94:95]
	v_pk_add_f32 v[88:89], v[82:83], v[92:93]
	s_waitcnt vmcnt(8)
	v_pk_fma_f32 v[26:27], v[86:87], v[102:103], v[98:99]
	v_pk_fma_f32 v[24:25], v[88:89], v[100:101], v[96:97]
	v_mul_f32_e32 v83, v27, v27
	v_mul_f32_e32 v82, v25, v25
	v_fmac_f32_e32 v82, v24, v24
	v_fmac_f32_e32 v83, v26, v26
	global_store_dwordx4 v[76:77], v[24:27], off offset:2048
	v_add_f32_e32 v82, v82, v83
	v_add_f32_e32 v88, v90, v82
	s_nop 0
	s_waitcnt vmcnt(7)
	v_pk_add_f32 v[84:85], v[106:107], v[110:111]
	v_pk_add_f32 v[82:83], v[104:105], v[108:109]
	s_waitcnt vmcnt(6)
	v_pk_add_f32 v[30:31], v[84:85], v[114:115]
	v_pk_add_f32 v[82:83], v[82:83], v[112:113]
	s_waitcnt vmcnt(5)
	v_pk_add_f32 v[28:29], v[30:31], v[118:119]
	v_pk_add_f32 v[78:79], v[82:83], v[116:117]
	s_waitcnt vmcnt(3)
	v_pk_fma_f32 v[30:31], v[28:29], v[126:127], v[122:123]
	v_pk_fma_f32 v[28:29], v[78:79], v[124:125], v[120:121]
	global_store_dwordx4 v[76:77], v[28:31], off offset:3072
	v_mul_f32_e32 v76, v29, v29
	v_mul_f32_e32 v77, v31, v31
	v_fmac_f32_e32 v76, v28, v28
	v_fmac_f32_e32 v77, v30, v30
	v_add_f32_e32 v76, v76, v77
	v_add_f32_e32 v76, v88, v76
	ds_swizzle_b32 v77, v76 offset:swizzle(SWAP,1)
	s_waitcnt lgkmcnt(0)
	v_add_f32_e32 v76, v76, v77
	ds_swizzle_b32 v77, v76 offset:swizzle(SWAP,2)
	s_waitcnt lgkmcnt(0)
	v_add_f32_e32 v76, v76, v77
	ds_swizzle_b32 v77, v76 offset:swizzle(SWAP,4)
	s_waitcnt lgkmcnt(0)
	v_add_f32_e32 v76, v76, v77
	ds_swizzle_b32 v77, v76 offset:swizzle(SWAP,8)
	s_waitcnt lgkmcnt(0)
	v_add_f32_e32 v76, v76, v77
	ds_swizzle_b32 v77, v76 offset:swizzle(SWAP,16)
	s_waitcnt lgkmcnt(0)
	v_add_f32_e32 v76, v76, v77
	v_mbcnt_lo_u32_b32 v77, -1, 0
	v_mbcnt_hi_u32_b32 v77, -1, v77
	s_nop 0
	v_lshlrev_b32_e32 v77, 2, v77
	v_xor_b32_e32 v77, 0x80, v77
	ds_bpermute_b32 v77, v77, v76
	s_and_saveexec_b64 s[18:19], s[0:1]
	s_cbranch_execz .LBB0_170
	s_waitcnt lgkmcnt(0)
	v_add_f32_e32 v76, v76, v77
	v_fmamk_f32 v76, v76, 0x3a000000, v250
	v_cmp_gt_f32_e32 vcc, s97, v76
	v_mul_f32_e32 v77, 0x4f800000, v76
	s_nop 0
	v_cndmask_b32_e32 v76, v76, v77, vcc
	v_sqrt_f32_e32 v77, v76
	s_nop 0
	v_add_u32_e32 v78, -1, v77
	v_fma_f32 v79, -v78, v77, v76
	v_cmp_ge_f32_e64 s[4:5], 0, v79
	v_add_u32_e32 v79, 1, v77
	s_nop 0
	v_cndmask_b32_e64 v78, v77, v78, s[4:5]
	v_fma_f32 v77, -v79, v77, v76
	v_cmp_lt_f32_e64 s[4:5], 0, v77
	s_nop 1
	v_cndmask_b32_e64 v77, v78, v79, s[4:5]
	v_mul_f32_e32 v78, 0x37800000, v77
	v_cndmask_b32_e32 v77, v77, v78, vcc
	v_cmp_class_f32_e32 vcc, v76, v251
	s_nop 1
	v_cndmask_b32_e32 v76, v77, v76, vcc
	v_div_scale_f32 v77, s[4:5], v76, v76, 1.0
	v_rcp_f32_e32 v78, v77
	s_nop 0
	v_fma_f32 v79, -v77, v78, 1.0
	v_fmac_f32_e32 v78, v79, v78
	v_div_scale_f32 v79, vcc, 1.0, v76, 1.0
	v_mul_f32_e32 v80, v79, v78
	v_fma_f32 v81, -v77, v80, v79
	v_fmac_f32_e32 v80, v81, v78
	v_fma_f32 v77, -v77, v80, v79
	v_div_fmas_f32 v77, v77, v78, v80
	v_div_fixup_f32 v76, v77, v76, 1.0
	v_mov_b32 v77, 0
	s_nop 0
	v_add_u32_e32 v77, s79, v77
	ds_read_b32 v78, v77 offset:280
	ds_read_b32 v77, v77 offset:284
	s_waitcnt lgkmcnt(1)
	v_readfirstlane_b32 s4, v78
	s_waitcnt lgkmcnt(0)
	v_readfirstlane_b32 s5, v77
	s_add_u32 s4, s4, s20
	s_addc_u32 s5, s5, s21
	s_nop 2
	global_store_dword v209, v76, s[4:5]
	s_branch .LBB0_170

; #define MFMA16(a, b, c) __builtin_amdgcn_mfma_f32_16x16x32_bf16((a), (b), (c), 0, 0, 0)
; __device__ __forceinline__ void s5_out_unit(const PA& a, int unit, LAS unsigned char* lds, int tid_) {
;     ...
; #pragma unroll
;     for (int dir = 0; dir < 2; ++dir)
; #pragma unroll
;         for (int ks = 0; ks < 4; ++ks) { bf16x8 bfr[3];
; #pragma unroll
;             for (int nt = 0; nt < 3; ++nt) bfr[nt] = *(const bf16x8*)(SI + (size_t)(nt * 16 * 32 * 2 + dir) * 128 + ks * 32);
; #pragma unroll
;             for (int i = 0; i < 8; ++i) { const bf16x8 af = *(const bf16x8*)(AC + (size_t)(dir * 1024 + i * 16) * 128 + ks * 32);
; #pragma unroll
;                 for (int nt = 0; nt < 3; ++nt) acc[i][nt] = MFMA16(af, bfr[nt], acc[i][nt]); } }
.LBB0_962:
	v_lshl_or_b32 v0, v128, 4, v129
	v_ashrrev_i32_e32 v1, 31, v0
	v_lshlrev_b64 v[0:1], 8, v[0:1]
	v_lshl_add_u64 v[0:1], s[0:1], 0, v[0:1]
	v_lshlrev_b32_e32 v2, 4, v132
	v_mov_b32_e32 v3, v209
	v_lshl_add_u64 v[138:139], v[0:1], 0, v[2:3]
	s_mov_b64 s[0:1], 0x90000
	s_mul_i32 s11, s11, 48
	v_lshl_add_u64 v[140:141], v[138:139], 0, s[0:1]
	v_or_b32_e32 v130, s11, v129
	s_lshl_b32 s0, s10, 1
	v_lshl_add_u32 v0, v130, 6, s0
	v_ashrrev_i32_e32 v1, 31, v0
	v_readfirstlane_b32 s5, v133
	v_lshlrev_b64 v[0:1], 8, v[0:1]
	s_mov_b64 s[0:1], 0x55000000
	v_lshl_add_u64 v[0:1], s[4:5], 0, v[0:1]
	v_lshl_add_u64 v[8:9], v[0:1], 0, v[2:3]
	v_lshlrev_b32_e32 v208, 3, v132
	v_lshl_add_u64 v[132:133], v[8:9], 0, s[0:1]
	s_mov_b32 s0, 0x55000000
	v_add_co_u32_e32 v0, vcc, s0, v8
	s_mov_b32 s0, 0x55040000
	s_nop 0
	v_addc_co_u32_e32 v1, vcc, 0, v9, vcc
	v_add_co_u32_e32 v134, vcc, s0, v8
	s_mov_b32 s0, 0x55080000
	s_nop 0
	v_addc_co_u32_e32 v135, vcc, 0, v9, vcc
	v_add_co_u32_e32 v136, vcc, s0, v8
	s_mov_b32 s0, 0x91000
	s_nop 0
	v_addc_co_u32_e32 v137, vcc, 0, v9, vcc
	v_add_co_u32_e32 v150, vcc, s0, v138
	global_load_dwordx4 v[0:3], v[0:1], off
	s_nop 0
	v_addc_co_u32_e32 v151, vcc, 0, v139, vcc
	global_load_dwordx4 v[12:15], v[150:151], off offset:-4096
	global_load_dwordx4 v[24:27], v[150:151], off
	global_load_dwordx4 v[4:7], v[134:135], off
	global_load_dwordx4 v[8:11], v[136:137], off
	s_mov_b32 s0, 0x92000
	v_ashrrev_i32_e32 v131, 31, v130
	v_ashrrev_i32_e32 v129, 31, v128
	s_waitcnt vmcnt(3)
	v_mfma_f32_16x16x32_bf16 v[16:19], v[12:15], v[0:3], v[124:127]
	s_nop 2
	v_add_co_u32_e32 v124, vcc, s0, v138
	s_mov_b32 s0, 0x93000
	s_nop 0
	v_addc_co_u32_e32 v125, vcc, 0, v139, vcc
	v_add_co_u32_e32 v126, vcc, s0, v138
	s_waitcnt vmcnt(2)
	v_mfma_f32_16x16x32_bf16 v[28:31], v[24:27], v[0:3], v[112:115]
	v_addc_co_u32_e32 v127, vcc, 0, v139, vcc
	s_mov_b32 s0, 0x94000
	s_waitcnt vmcnt(1)
	v_mfma_f32_16x16x32_bf16 v[108:111], v[24:27], v[4:7], v[108:111]
	v_add_co_u32_e32 v158, vcc, s0, v138
	s_mov_b32 s0, 0x95000
	s_waitcnt vmcnt(0)
	v_mfma_f32_16x16x32_bf16 v[24:27], v[24:27], v[8:11], v[104:107]
	v_addc_co_u32_e32 v159, vcc, 0, v139, vcc
	v_add_co_u32_e32 v170, vcc, s0, v138
	s_nop 0
	global_load_dwordx4 v[104:107], v[126:127], off offset:-4096
	v_addc_co_u32_e32 v171, vcc, 0, v139, vcc
	s_mov_b32 s0, 0x96000
	v_add_co_u32_e32 v182, vcc, s0, v138
	s_mov_b32 s0, 0x97000
	s_nop 0
	v_addc_co_u32_e32 v183, vcc, 0, v139, vcc
	v_add_co_u32_e32 v184, vcc, s0, v138
	v_mfma_f32_16x16x32_bf16 v[20:23], v[12:15], v[4:7], v[120:123]
	s_nop 0
	v_addc_co_u32_e32 v185, vcc, 0, v139, vcc
	global_load_dwordx4 v[222:225], v[126:127], off
	global_load_dwordx4 v[226:229], v[170:171], off offset:-4096
	global_load_dwordx4 v[230:233], v[170:171], off
	global_load_dwordx4 v[234:237], v[184:185], off offset:-4096
	global_load_dwordx4 v[238:241], v[184:185], off
	s_mov_b32 s0, 0xd0000
	v_mfma_f32_16x16x32_bf16 v[12:15], v[12:15], v[8:11], v[116:119]
	s_waitcnt vmcnt(5)
	v_mfma_f32_16x16x32_bf16 v[100:103], v[104:107], v[0:3], v[100:103]
	v_mfma_f32_16x16x32_bf16 v[96:99], v[104:107], v[4:7], v[96:99]
	v_mfma_f32_16x16x32_bf16 v[92:95], v[104:107], v[8:11], v[92:95]
	s_waitcnt vmcnt(4)
	v_mfma_f32_16x16x32_bf16 v[88:91], v[222:225], v[0:3], v[88:91]
	v_mfma_f32_16x16x32_bf16 v[84:87], v[222:225], v[4:7], v[84:87]
	v_mfma_f32_16x16x32_bf16 v[80:83], v[222:225], v[8:11], v[80:83]
	s_waitcnt vmcnt(3)
	v_mfma_f32_16x16x32_bf16 v[76:79], v[226:229], v[0:3], v[76:79]
	v_mfma_f32_16x16x32_bf16 v[72:75], v[226:229], v[4:7], v[72:75]
	v_mfma_f32_16x16x32_bf16 v[68:71], v[226:229], v[8:11], v[68:71]
	s_waitcnt vmcnt(2)
	v_mfma_f32_16x16x32_bf16 v[64:67], v[230:233], v[0:3], v[64:67]
	v_mfma_f32_16x16x32_bf16 v[60:63], v[230:233], v[4:7], v[60:63]
	v_mfma_f32_16x16x32_bf16 v[56:59], v[230:233], v[8:11], v[56:59]
	s_waitcnt vmcnt(1)
	v_mfma_f32_16x16x32_bf16 v[52:55], v[234:237], v[0:3], v[52:55]
	v_mfma_f32_16x16x32_bf16 v[48:51], v[234:237], v[4:7], v[48:51]
	v_mfma_f32_16x16x32_bf16 v[44:47], v[234:237], v[8:11], v[44:47]
	s_waitcnt vmcnt(0)
	v_mfma_f32_16x16x32_bf16 v[0:3], v[238:241], v[0:3], v[40:43]
	v_mfma_f32_16x16x32_bf16 v[4:7], v[238:241], v[4:7], v[36:39]
	v_mfma_f32_16x16x32_bf16 v[8:11], v[238:241], v[8:11], v[32:35]
	s_nop 2
	global_load_dwordx4 v[32:35], v[132:133], off offset:64
	global_load_dwordx4 v[36:39], v[134:135], off offset:64
	global_load_dwordx4 v[40:43], v[136:137], off offset:64
	global_load_dwordx4 v[210:213], v[140:141], off offset:64
	global_load_dwordx4 v[214:217], v[150:151], off offset:64
	global_load_dwordx4 v[218:221], v[124:125], off offset:64
	global_load_dwordx4 v[222:225], v[126:127], off offset:64
	global_load_dwordx4 v[226:229], v[158:159], off offset:64
	global_load_dwordx4 v[230:233], v[170:171], off offset:64
	global_load_dwordx4 v[234:237], v[182:183], off offset:64
	global_load_dwordx4 v[238:241], v[184:185], off offset:64
	s_waitcnt vmcnt(7)
	v_mfma_f32_16x16x32_bf16 v[16:19], v[210:213], v[32:35], v[16:19]
	v_mfma_f32_16x16x32_bf16 v[20:23], v[210:213], v[36:39], v[20:23]
	v_mfma_f32_16x16x32_bf16 v[12:15], v[210:213], v[40:43], v[12:15]
	s_waitcnt vmcnt(6)
	v_mfma_f32_16x16x32_bf16 v[28:31], v[214:217], v[32:35], v[28:31]
	v_mfma_f32_16x16x32_bf16 v[108:111], v[214:217], v[36:39], v[108:111]
	v_mfma_f32_16x16x32_bf16 v[24:27], v[214:217], v[40:43], v[24:27]
	s_waitcnt vmcnt(5)
	v_mfma_f32_16x16x32_bf16 v[100:103], v[218:221], v[32:35], v[100:103]
	v_mfma_f32_16x16x32_bf16 v[96:99], v[218:221], v[36:39], v[96:99]
	v_mfma_f32_16x16x32_bf16 v[92:95], v[218:221], v[40:43], v[92:95]
	s_waitcnt vmcnt(4)
; #define MFMA16(a, b, c) __builtin_amdgcn_mfma_f32_16x16x32_bf16((a), (b), (c), 0, 0, 0)
; __device__ __forceinline__ void s5_out_unit(const PA& a, int unit, LAS unsigned char* lds, int tid_) {
;     ...
;         for (int ks = 0; ks < 4; ++ks) { bf16x8 bfr[3];
; #pragma unroll
;             for (int nt = 0; nt < 3; ++nt) bfr[nt] = *(const bf16x8*)(SI + (size_t)(nt * 16 * 32 * 2 + dir) * 128 + ks * 32);
; #pragma unroll
;             for (int i = 0; i < 8; ++i) { const bf16x8 af = *(const bf16x8*)(AC + (size_t)(dir * 1024 + i * 16) * 128 + ks * 32);
; #pragma unroll
;                 for (int nt = 0; nt < 3; ++nt) acc[i][nt] = MFMA16(af, bfr[nt], acc[i][nt]); } }
	v_mfma_f32_16x16x32_bf16 v[88:91], v[222:225], v[32:35], v[88:91]
	v_mfma_f32_16x16x32_bf16 v[84:87], v[222:225], v[36:39], v[84:87]
	v_mfma_f32_16x16x32_bf16 v[80:83], v[222:225], v[40:43], v[80:83]
	s_waitcnt vmcnt(3)
	v_mfma_f32_16x16x32_bf16 v[76:79], v[226:229], v[32:35], v[76:79]
	v_mfma_f32_16x16x32_bf16 v[72:75], v[226:229], v[36:39], v[72:75]
	v_mfma_f32_16x16x32_bf16 v[68:71], v[226:229], v[40:43], v[68:71]
	s_waitcnt vmcnt(2)
	v_mfma_f32_16x16x32_bf16 v[64:67], v[230:233], v[32:35], v[64:67]
	v_mfma_f32_16x16x32_bf16 v[60:63], v[230:233], v[36:39], v[60:63]
	v_mfma_f32_16x16x32_bf16 v[56:59], v[230:233], v[40:43], v[56:59]
	s_waitcnt vmcnt(1)
	v_mfma_f32_16x16x32_bf16 v[52:55], v[234:237], v[32:35], v[52:55]
	v_mfma_f32_16x16x32_bf16 v[48:51], v[234:237], v[36:39], v[48:51]
	v_mfma_f32_16x16x32_bf16 v[44:47], v[234:237], v[40:43], v[44:47]
	s_waitcnt vmcnt(0)
	v_mfma_f32_16x16x32_bf16 v[0:3], v[238:241], v[32:35], v[0:3]
	v_mfma_f32_16x16x32_bf16 v[4:7], v[238:241], v[36:39], v[4:7]
	v_mfma_f32_16x16x32_bf16 v[8:11], v[238:241], v[40:43], v[8:11]
	global_load_dwordx4 v[32:35], v[132:133], off offset:128
	global_load_dwordx4 v[36:39], v[134:135], off offset:128
	global_load_dwordx4 v[40:43], v[136:137], off offset:128
	global_load_dwordx4 v[210:213], v[140:141], off offset:128
	global_load_dwordx4 v[214:217], v[150:151], off offset:128
	global_load_dwordx4 v[218:221], v[124:125], off offset:128
	global_load_dwordx4 v[222:225], v[126:127], off offset:128
	global_load_dwordx4 v[226:229], v[158:159], off offset:128
	global_load_dwordx4 v[230:233], v[170:171], off offset:128
	global_load_dwordx4 v[234:237], v[182:183], off offset:128
	global_load_dwordx4 v[238:241], v[184:185], off offset:128
	s_waitcnt vmcnt(7)
	v_mfma_f32_16x16x32_bf16 v[16:19], v[210:213], v[32:35], v[16:19]
	v_mfma_f32_16x16x32_bf16 v[20:23], v[210:213], v[36:39], v[20:23]
	v_mfma_f32_16x16x32_bf16 v[12:15], v[210:213], v[40:43], v[12:15]
	s_waitcnt vmcnt(6)
	v_mfma_f32_16x16x32_bf16 v[28:31], v[214:217], v[32:35], v[28:31]
	v_mfma_f32_16x16x32_bf16 v[108:111], v[214:217], v[36:39], v[108:111]
	v_mfma_f32_16x16x32_bf16 v[24:27], v[214:217], v[40:43], v[24:27]
	s_waitcnt vmcnt(5)
	v_mfma_f32_16x16x32_bf16 v[100:103], v[218:221], v[32:35], v[100:103]
	v_mfma_f32_16x16x32_bf16 v[96:99], v[218:221], v[36:39], v[96:99]
	v_mfma_f32_16x16x32_bf16 v[92:95], v[218:221], v[40:43], v[92:95]
	s_waitcnt vmcnt(4)
	v_mfma_f32_16x16x32_bf16 v[88:91], v[222:225], v[32:35], v[88:91]
	v_mfma_f32_16x16x32_bf16 v[84:87], v[222:225], v[36:39], v[84:87]
	v_mfma_f32_16x16x32_bf16 v[80:83], v[222:225], v[40:43], v[80:83]
	s_waitcnt vmcnt(3)
	v_mfma_f32_16x16x32_bf16 v[76:79], v[226:229], v[32:35], v[76:79]
	v_mfma_f32_16x16x32_bf16 v[72:75], v[226:229], v[36:39], v[72:75]
	v_mfma_f32_16x16x32_bf16 v[68:71], v[226:229], v[40:43], v[68:71]
	s_waitcnt vmcnt(2)
	v_mfma_f32_16x16x32_bf16 v[64:67], v[230:233], v[32:35], v[64:67]
	v_mfma_f32_16x16x32_bf16 v[60:63], v[230:233], v[36:39], v[60:63]
	v_mfma_f32_16x16x32_bf16 v[56:59], v[230:233], v[40:43], v[56:59]
	s_waitcnt vmcnt(1)
	v_mfma_f32_16x16x32_bf16 v[52:55], v[234:237], v[32:35], v[52:55]
	v_mfma_f32_16x16x32_bf16 v[48:51], v[234:237], v[36:39], v[48:51]
	v_mfma_f32_16x16x32_bf16 v[44:47], v[234:237], v[40:43], v[44:47]
	s_waitcnt vmcnt(0)
	v_mfma_f32_16x16x32_bf16 v[32:35], v[238:241], v[32:35], v[0:3]
	v_mfma_f32_16x16x32_bf16 v[36:39], v[238:241], v[36:39], v[4:7]
	v_mfma_f32_16x16x32_bf16 v[40:43], v[238:241], v[40:43], v[8:11]
	global_load_dwordx4 v[104:107], v[132:133], off offset:192
	global_load_dwordx4 v[112:115], v[134:135], off offset:192
	global_load_dwordx4 v[116:119], v[136:137], off offset:192
	global_load_dwordx4 v[210:213], v[140:141], off offset:192
	global_load_dwordx4 v[214:217], v[182:183], off offset:192
	global_load_dwordx4 v[218:221], v[150:151], off offset:192
	global_load_dwordx4 v[222:225], v[184:185], off offset:192
	global_load_dwordx4 v[226:229], v[124:125], off offset:192
	global_load_dwordx4 v[230:233], v[126:127], off offset:192
	global_load_dwordx4 v[234:237], v[158:159], off offset:192
	global_load_dwordx4 v[238:241], v[170:171], off offset:192
	s_waitcnt vmcnt(7)
	v_mfma_f32_16x16x32_bf16 v[120:123], v[210:213], v[104:107], v[16:19]
	v_mfma_f32_16x16x32_bf16 v[140:143], v[210:213], v[112:115], v[20:23]
	v_mfma_f32_16x16x32_bf16 v[144:147], v[210:213], v[116:119], v[12:15]
	s_nop 0
	s_waitcnt vmcnt(5)
	v_mfma_f32_16x16x32_bf16 v[150:153], v[218:221], v[104:107], v[28:31]
	v_mfma_f32_16x16x32_bf16 v[108:111], v[218:221], v[112:115], v[108:111]
	v_mfma_f32_16x16x32_bf16 v[154:157], v[218:221], v[116:119], v[24:27]
	s_waitcnt vmcnt(3)
	v_mfma_f32_16x16x32_bf16 v[100:103], v[226:229], v[104:107], v[100:103]
	v_mfma_f32_16x16x32_bf16 v[96:99], v[226:229], v[112:115], v[96:99]
	v_mfma_f32_16x16x32_bf16 v[92:95], v[226:229], v[116:119], v[92:95]
	v_add_co_u32_e32 v126, vcc, s0, v138
	s_waitcnt vmcnt(2)
	v_mfma_f32_16x16x32_bf16 v[88:91], v[230:233], v[104:107], v[88:91]
	v_addc_co_u32_e32 v127, vcc, 0, v139, vcc
	s_mov_b32 s0, 0xd1000
	v_mfma_f32_16x16x32_bf16 v[84:87], v[230:233], v[112:115], v[84:87]
	v_add_co_u32_e32 v124, vcc, s0, v138
	s_mov_b32 s0, 0xd2000
	v_mfma_f32_16x16x32_bf16 v[80:83], v[230:233], v[116:119], v[80:83]
	v_addc_co_u32_e32 v125, vcc, 0, v139, vcc
	s_waitcnt vmcnt(1)
	v_mfma_f32_16x16x32_bf16 v[158:161], v[234:237], v[104:107], v[76:79]
	v_mfma_f32_16x16x32_bf16 v[162:165], v[234:237], v[112:115], v[72:75]
	v_mfma_f32_16x16x32_bf16 v[166:169], v[234:237], v[116:119], v[68:71]
	s_waitcnt vmcnt(0)
; #define MFMA16(a, b, c) __builtin_amdgcn_mfma_f32_16x16x32_bf16((a), (b), (c), 0, 0, 0)
; __device__ __forceinline__ void s5_out_unit(const PA& a, int unit, LAS unsigned char* lds, int tid_) {
;     ...
;         for (int ks = 0; ks < 4; ++ks) { bf16x8 bfr[3];
; #pragma unroll
;             for (int nt = 0; nt < 3; ++nt) bfr[nt] = *(const bf16x8*)(SI + (size_t)(nt * 16 * 32 * 2 + dir) * 128 + ks * 32);
; #pragma unroll
;             for (int i = 0; i < 8; ++i) { const bf16x8 af = *(const bf16x8*)(AC + (size_t)(dir * 1024 + i * 16) * 128 + ks * 32);
; #pragma unroll
;                 for (int nt = 0; nt < 3; ++nt) acc[i][nt] = MFMA16(af, bfr[nt], acc[i][nt]); } }
	v_mfma_f32_16x16x32_bf16 v[170:173], v[238:241], v[104:107], v[64:67]
	v_mfma_f32_16x16x32_bf16 v[174:177], v[238:241], v[112:115], v[60:63]
	v_mfma_f32_16x16x32_bf16 v[178:181], v[238:241], v[116:119], v[56:59]
	v_mfma_f32_16x16x32_bf16 v[0:3], v[214:217], v[104:107], v[52:55]
	v_mfma_f32_16x16x32_bf16 v[4:7], v[214:217], v[112:115], v[48:51]
	v_mfma_f32_16x16x32_bf16 v[8:11], v[214:217], v[116:119], v[44:47]
	v_mfma_f32_16x16x32_bf16 v[12:15], v[222:225], v[104:107], v[32:35]
	global_load_dwordx4 v[24:27], v[132:133], off offset:256
	global_load_dwordx4 v[28:31], v[134:135], off offset:256
	s_nop 0
	global_load_dwordx4 v[32:35], v[136:137], off offset:256
	global_load_dwordx4 v[44:47], v[124:125], off offset:-4096
	global_load_dwordx4 v[56:59], v[124:125], off
	v_mfma_f32_16x16x32_bf16 v[16:19], v[222:225], v[112:115], v[36:39]
	v_mfma_f32_16x16x32_bf16 v[20:23], v[222:225], v[116:119], v[40:43]
	s_waitcnt vmcnt(1)
	v_mfma_f32_16x16x32_bf16 v[40:43], v[44:47], v[28:31], v[140:143]
	s_nop 2
	v_add_co_u32_e32 v142, vcc, s0, v138
	s_mov_b32 s0, 0xd3000
	s_nop 0
	v_addc_co_u32_e32 v143, vcc, 0, v139, vcc
	v_add_co_u32_e32 v140, vcc, s0, v138
	s_mov_b32 s0, 0xd4000
	s_nop 0
	v_addc_co_u32_e32 v141, vcc, 0, v139, vcc
	global_load_dwordx4 v[68:71], v[140:141], off offset:-4096
	v_mfma_f32_16x16x32_bf16 v[36:39], v[44:47], v[24:27], v[120:123]
	v_mfma_f32_16x16x32_bf16 v[44:47], v[44:47], v[32:35], v[144:147]
	s_nop 2
	v_add_co_u32_e32 v146, vcc, s0, v138
	s_mov_b32 s0, 0xd5000
	s_nop 0
	v_addc_co_u32_e32 v147, vcc, 0, v139, vcc
	v_add_co_u32_e32 v144, vcc, s0, v138
	s_mov_b32 s0, 0xd6000
	s_nop 0
	v_addc_co_u32_e32 v145, vcc, 0, v139, vcc
	v_add_co_u32_e32 v122, vcc, s0, v138
	s_mov_b32 s0, 0xd7000
	s_nop 0
	v_addc_co_u32_e32 v123, vcc, 0, v139, vcc
	v_add_co_u32_e32 v120, vcc, s0, v138
	s_waitcnt vmcnt(1)
	v_mfma_f32_16x16x32_bf16 v[52:55], v[56:59], v[28:31], v[108:111]
	v_addc_co_u32_e32 v121, vcc, 0, v139, vcc
	global_load_dwordx4 v[104:107], v[144:145], off
	s_nop 0
	global_load_dwordx4 v[108:111], v[120:121], off offset:-4096
	global_load_dwordx4 v[230:233], v[140:141], off
	global_load_dwordx4 v[234:237], v[120:121], off
	global_load_dwordx4 v[238:241], v[144:145], off offset:-4096
	s_waitcnt vmcnt(5)
	v_mfma_f32_16x16x32_bf16 v[60:63], v[68:71], v[24:27], v[100:103]
	s_lshl_b32 s0, s10, 4
	s_ashr_i32 s1, s0, 31
	s_lshl_b64 s[0:1], s[0:1], 1
	v_mfma_f32_16x16x32_bf16 v[64:67], v[68:71], v[28:31], v[96:99]
	v_mfma_f32_16x16x32_bf16 v[68:71], v[68:71], v[32:35], v[92:95]
	s_nop 2
	s_waitcnt vmcnt(3)
	v_mfma_f32_16x16x32_bf16 v[0:3], v[108:111], v[24:27], v[0:3]
	v_mfma_f32_16x16x32_bf16 v[4:7], v[108:111], v[28:31], v[4:7]
	v_mfma_f32_16x16x32_bf16 v[8:11], v[108:111], v[32:35], v[8:11]
	s_waitcnt vmcnt(2)
	v_mfma_f32_16x16x32_bf16 v[72:75], v[230:233], v[24:27], v[88:91]
	v_mfma_f32_16x16x32_bf16 v[76:79], v[230:233], v[28:31], v[84:87]
	v_mfma_f32_16x16x32_bf16 v[80:83], v[230:233], v[32:35], v[80:83]
	v_mfma_f32_16x16x32_bf16 v[48:51], v[56:59], v[24:27], v[150:153]
	v_mfma_f32_16x16x32_bf16 v[56:59], v[56:59], v[32:35], v[154:157]
	s_waitcnt vmcnt(0)
	v_mfma_f32_16x16x32_bf16 v[84:87], v[238:241], v[24:27], v[158:161]
	v_mfma_f32_16x16x32_bf16 v[88:91], v[238:241], v[28:31], v[162:165]
	v_mfma_f32_16x16x32_bf16 v[92:95], v[238:241], v[32:35], v[166:169]
	v_mfma_f32_16x16x32_bf16 v[96:99], v[104:107], v[24:27], v[170:173]
	v_mfma_f32_16x16x32_bf16 v[100:103], v[104:107], v[28:31], v[174:177]
	v_mfma_f32_16x16x32_bf16 v[104:107], v[104:107], v[32:35], v[178:181]
	v_mfma_f32_16x16x32_bf16 v[12:15], v[234:237], v[24:27], v[12:15]
	v_mfma_f32_16x16x32_bf16 v[16:19], v[234:237], v[28:31], v[16:19]
	v_mfma_f32_16x16x32_bf16 v[20:23], v[234:237], v[32:35], v[20:23]
	global_load_dwordx4 v[24:27], v[132:133], off offset:320
	global_load_dwordx4 v[28:31], v[134:135], off offset:320
	global_load_dwordx4 v[32:35], v[136:137], off offset:320
	global_load_dwordx4 v[210:213], v[126:127], off offset:64
	global_load_dwordx4 v[214:217], v[124:125], off offset:64
	global_load_dwordx4 v[218:221], v[142:143], off offset:64
	global_load_dwordx4 v[222:225], v[140:141], off offset:64
	global_load_dwordx4 v[226:229], v[146:147], off offset:64
	global_load_dwordx4 v[230:233], v[144:145], off offset:64
	global_load_dwordx4 v[234:237], v[122:123], off offset:64
	global_load_dwordx4 v[238:241], v[120:121], off offset:64
	s_waitcnt vmcnt(7)
	v_mfma_f32_16x16x32_bf16 v[36:39], v[210:213], v[24:27], v[36:39]
	v_mfma_f32_16x16x32_bf16 v[40:43], v[210:213], v[28:31], v[40:43]
	v_mfma_f32_16x16x32_bf16 v[44:47], v[210:213], v[32:35], v[44:47]
	s_waitcnt vmcnt(6)
	v_mfma_f32_16x16x32_bf16 v[48:51], v[214:217], v[24:27], v[48:51]
	v_mfma_f32_16x16x32_bf16 v[52:55], v[214:217], v[28:31], v[52:55]
	v_mfma_f32_16x16x32_bf16 v[56:59], v[214:217], v[32:35], v[56:59]
	s_waitcnt vmcnt(5)
	v_mfma_f32_16x16x32_bf16 v[60:63], v[218:221], v[24:27], v[60:63]
	v_mfma_f32_16x16x32_bf16 v[64:67], v[218:221], v[28:31], v[64:67]
	v_mfma_f32_16x16x32_bf16 v[68:71], v[218:221], v[32:35], v[68:71]
	s_waitcnt vmcnt(4)
	v_mfma_f32_16x16x32_bf16 v[72:75], v[222:225], v[24:27], v[72:75]
	v_mfma_f32_16x16x32_bf16 v[76:79], v[222:225], v[28:31], v[76:79]
	v_mfma_f32_16x16x32_bf16 v[80:83], v[222:225], v[32:35], v[80:83]
	s_waitcnt vmcnt(3)
	v_mfma_f32_16x16x32_bf16 v[84:87], v[226:229], v[24:27], v[84:87]
	v_mfma_f32_16x16x32_bf16 v[88:91], v[226:229], v[28:31], v[88:91]
	v_mfma_f32_16x16x32_bf16 v[92:95], v[226:229], v[32:35], v[92:95]
	s_waitcnt vmcnt(2)
	v_mfma_f32_16x16x32_bf16 v[96:99], v[230:233], v[24:27], v[96:99]
	v_mfma_f32_16x16x32_bf16 v[100:103], v[230:233], v[28:31], v[100:103]
	v_mfma_f32_16x16x32_bf16 v[104:107], v[230:233], v[32:35], v[104:107]
	s_waitcnt vmcnt(1)
; __device__ __forceinline__ unsigned pk2(float lo, float hi) { const f32x2 v = {lo, hi}; return __builtin_bit_cast(unsigned, __builtin_convertvector(v, bf16x2_t)); }
; __device__ __forceinline__ float gelu_tanh(float x) { const float y = 0.7978845608028654f * (x + 0.044715f * x * x * x); return x * sigmoidf_(2.f * y); }
;     __device__ __forceinline__ unsigned char* ws() const { return (unsigned char*)(__attribute__((address_space(1))) unsigned char*)get(35); }
; #define MFMA16(a, b, c) __builtin_amdgcn_mfma_f32_16x16x32_bf16((a), (b), (c), 0, 0, 0)
; __device__ __forceinline__ void s5_out_unit(const PA& a, int unit, LAS unsigned char* lds, int tid_) {
;     ...
;         for (int ks = 0; ks < 4; ++ks) { bf16x8 bfr[3];
; #pragma unroll
;             for (int nt = 0; nt < 3; ++nt) bfr[nt] = *(const bf16x8*)(SI + (size_t)(nt * 16 * 32 * 2 + dir) * 128 + ks * 32);
; #pragma unroll
;             for (int i = 0; i < 8; ++i) { const bf16x8 af = *(const bf16x8*)(AC + (size_t)(dir * 1024 + i * 16) * 128 + ks * 32);
; #pragma unroll
;                 for (int nt = 0; nt < 3; ++nt) acc[i][nt] = MFMA16(af, bfr[nt], acc[i][nt]); } }
;     bf16* YG = (bf16*)(a.ws() + WS_YG);
; #pragma unroll
;     for (int i = 0; i < 8; ++i)
; #pragma unroll
;         for (int nt = 0; nt < 3; ++nt) { const int chunk = nb * 48 + nt * 16 + fr; const size_t row = (size_t)chunk * 64 + 8 * w + i; const f32x4 v = acc[i][nt];
;             *(u32x2*)(YG + row * 512 + g * 16 + kg * 4) = (u32x2){pk2(gelu_tanh(v.x), gelu_tanh(v.y)), pk2(gelu_tanh(v.z), gelu_tanh(v.w))}; }
	v_mfma_f32_16x16x32_bf16 v[0:3], v[234:237], v[24:27], v[0:3]
	v_mfma_f32_16x16x32_bf16 v[4:7], v[234:237], v[28:31], v[4:7]
	v_mfma_f32_16x16x32_bf16 v[8:11], v[234:237], v[32:35], v[8:11]
	s_waitcnt vmcnt(0)
	v_mfma_f32_16x16x32_bf16 v[24:27], v[238:241], v[24:27], v[12:15]
	v_mfma_f32_16x16x32_bf16 v[16:19], v[238:241], v[28:31], v[16:19]
	v_mfma_f32_16x16x32_bf16 v[20:23], v[238:241], v[32:35], v[20:23]
	global_load_dwordx4 v[28:31], v[132:133], off offset:384
	global_load_dwordx4 v[32:35], v[134:135], off offset:384
	global_load_dwordx4 v[108:111], v[136:137], off offset:384
	global_load_dwordx4 v[210:213], v[126:127], off offset:128
	global_load_dwordx4 v[214:217], v[124:125], off offset:128
	global_load_dwordx4 v[218:221], v[142:143], off offset:128
	global_load_dwordx4 v[222:225], v[140:141], off offset:128
	global_load_dwordx4 v[226:229], v[146:147], off offset:128
	global_load_dwordx4 v[230:233], v[144:145], off offset:128
	global_load_dwordx4 v[234:237], v[122:123], off offset:128
	global_load_dwordx4 v[238:241], v[120:121], off offset:128
	s_waitcnt vmcnt(7)
	v_mfma_f32_16x16x32_bf16 v[36:39], v[210:213], v[28:31], v[36:39]
	v_mfma_f32_16x16x32_bf16 v[40:43], v[210:213], v[32:35], v[40:43]
	v_mfma_f32_16x16x32_bf16 v[44:47], v[210:213], v[108:111], v[44:47]
	s_waitcnt vmcnt(6)
	v_mfma_f32_16x16x32_bf16 v[48:51], v[214:217], v[28:31], v[48:51]
	v_mfma_f32_16x16x32_bf16 v[52:55], v[214:217], v[32:35], v[52:55]
	v_mfma_f32_16x16x32_bf16 v[56:59], v[214:217], v[108:111], v[56:59]
	s_waitcnt vmcnt(5)
	v_mfma_f32_16x16x32_bf16 v[60:63], v[218:221], v[28:31], v[60:63]
	v_mfma_f32_16x16x32_bf16 v[64:67], v[218:221], v[32:35], v[64:67]
	v_mfma_f32_16x16x32_bf16 v[150:153], v[218:221], v[108:111], v[68:71]
	s_waitcnt vmcnt(4)
	v_mfma_f32_16x16x32_bf16 v[154:157], v[222:225], v[28:31], v[72:75]
	v_mfma_f32_16x16x32_bf16 v[158:161], v[222:225], v[32:35], v[76:79]
	v_mfma_f32_16x16x32_bf16 v[162:165], v[222:225], v[108:111], v[80:83]
	s_waitcnt vmcnt(3)
	v_mfma_f32_16x16x32_bf16 v[166:169], v[226:229], v[28:31], v[84:87]
	v_mfma_f32_16x16x32_bf16 v[170:173], v[226:229], v[32:35], v[88:91]
	v_mfma_f32_16x16x32_bf16 v[174:177], v[226:229], v[108:111], v[92:95]
	s_waitcnt vmcnt(2)
	v_mfma_f32_16x16x32_bf16 v[178:181], v[230:233], v[28:31], v[96:99]
	v_mfma_f32_16x16x32_bf16 v[182:185], v[230:233], v[32:35], v[100:103]
	v_mfma_f32_16x16x32_bf16 v[186:189], v[230:233], v[108:111], v[104:107]
	s_waitcnt vmcnt(1)
	v_mfma_f32_16x16x32_bf16 v[0:3], v[234:237], v[28:31], v[0:3]
	v_mfma_f32_16x16x32_bf16 v[4:7], v[234:237], v[32:35], v[4:7]
	v_mfma_f32_16x16x32_bf16 v[12:15], v[234:237], v[108:111], v[8:11]
	s_nop 2
	s_waitcnt vmcnt(0)
	v_mfma_f32_16x16x32_bf16 v[96:99], v[238:241], v[28:31], v[24:27]
	v_mfma_f32_16x16x32_bf16 v[100:103], v[238:241], v[32:35], v[16:19]
	v_mfma_f32_16x16x32_bf16 v[104:107], v[238:241], v[108:111], v[20:23]
	global_load_dwordx4 v[108:111], v[132:133], off offset:448
	global_load_dwordx4 v[112:115], v[134:135], off offset:448
	global_load_dwordx4 v[116:119], v[136:137], off offset:448
	global_load_dwordx4 v[8:11], v[126:127], off offset:192
	global_load_dwordx4 v[20:23], v[122:123], off offset:192
	global_load_dwordx4 v[210:213], v[124:125], off offset:192
	global_load_dwordx4 v[214:217], v[120:121], off offset:192
	global_load_dwordx4 v[218:221], v[142:143], off offset:192
	global_load_dwordx4 v[222:225], v[140:141], off offset:192
	global_load_dwordx4 v[226:229], v[146:147], off offset:192
	global_load_dwordx4 v[230:233], v[144:145], off offset:192
	s_waitcnt vmcnt(7)
	v_mfma_f32_16x16x32_bf16 v[92:95], v[8:11], v[108:111], v[36:39]
	v_mfma_f32_16x16x32_bf16 v[88:91], v[8:11], v[112:115], v[40:43]
	v_mfma_f32_16x16x32_bf16 v[84:87], v[8:11], v[116:119], v[44:47]
	s_waitcnt vmcnt(6)
	v_mfma_f32_16x16x32_bf16 v[36:39], v[20:23], v[108:111], v[0:3]
	s_nop 2
	s_waitcnt vmcnt(5)
	v_mfma_f32_16x16x32_bf16 v[80:83], v[210:213], v[108:111], v[48:51]
	v_mfma_f32_16x16x32_bf16 v[76:79], v[210:213], v[112:115], v[52:55]
	v_mfma_f32_16x16x32_bf16 v[72:75], v[210:213], v[116:119], v[56:59]
	s_waitcnt vmcnt(3)
	v_mfma_f32_16x16x32_bf16 v[68:71], v[218:221], v[108:111], v[60:63]
	v_mfma_f32_16x16x32_bf16 v[64:67], v[218:221], v[112:115], v[64:67]
	v_mfma_f32_16x16x32_bf16 v[60:63], v[218:221], v[116:119], v[150:153]
	s_waitcnt vmcnt(2)
	v_mfma_f32_16x16x32_bf16 v[56:59], v[222:225], v[108:111], v[154:157]
	v_mfma_f32_16x16x32_bf16 v[52:55], v[222:225], v[112:115], v[158:161]
	v_mfma_f32_16x16x32_bf16 v[48:51], v[222:225], v[116:119], v[162:165]
	v_mfma_f32_16x16x32_bf16 v[28:31], v[20:23], v[112:115], v[4:7]
	v_mfma_f32_16x16x32_bf16 v[20:23], v[20:23], v[116:119], v[12:15]
	v_mfma_f32_16x16x32_bf16 v[12:15], v[214:217], v[108:111], v[96:99]
	s_nop 2
	v_mul_f32_e32 v98, 0x3d372713, v92
	v_mul_f32_e32 v99, 0x3d372713, v93
	v_mul_f32_e32 v98, v92, v98
	v_mul_f32_e32 v99, v93, v99
	v_fma_f32 v98, v92, v98, v92
	v_fma_f32 v99, v93, v99, v93
	v_mul_f32_e32 v98, 0x3f4c422a, v98
	v_mul_f32_e32 v99, 0x3f4c422a, v99
	v_add_f32_e32 v98, v98, v98
	v_add_f32_e32 v99, v99, v99
	v_mul_f32_e32 v98, 0xbfb8aa3b, v98
	v_mul_f32_e32 v99, 0xbfb8aa3b, v99
	v_exp_f32_e32 v98, v98
	v_exp_f32_e32 v99, v99
	v_mfma_f32_16x16x32_bf16 v[4:7], v[214:217], v[112:115], v[100:103]
	v_add_f32_e32 v98, 1.0, v98
	v_add_f32_e32 v99, 1.0, v99
	v_rcp_f32_e32 v98, v98
	v_rcp_f32_e32 v99, v99
	s_waitcnt vmcnt(1)
; __device__ __forceinline__ unsigned pk2(float lo, float hi) { const f32x2 v = {lo, hi}; return __builtin_bit_cast(unsigned, __builtin_convertvector(v, bf16x2_t)); }
; __device__ __forceinline__ float gelu_tanh(float x) { const float y = 0.7978845608028654f * (x + 0.044715f * x * x * x); return x * sigmoidf_(2.f * y); }
;     __device__ __forceinline__ unsigned char* ws() const { return (unsigned char*)(__attribute__((address_space(1))) unsigned char*)get(35); }
; #define MFMA16(a, b, c) __builtin_amdgcn_mfma_f32_16x16x32_bf16((a), (b), (c), 0, 0, 0)
; __device__ __forceinline__ void s5_out_unit(const PA& a, int unit, LAS unsigned char* lds, int tid_) {
;     ...
;             for (int i = 0; i < 8; ++i) { const bf16x8 af = *(const bf16x8*)(AC + (size_t)(dir * 1024 + i * 16) * 128 + ks * 32);
; #pragma unroll
;                 for (int nt = 0; nt < 3; ++nt) acc[i][nt] = MFMA16(af, bfr[nt], acc[i][nt]); } }
;     bf16* YG = (bf16*)(a.ws() + WS_YG);
; #pragma unroll
;     for (int i = 0; i < 8; ++i)
; #pragma unroll
;         for (int nt = 0; nt < 3; ++nt) { const int chunk = nb * 48 + nt * 16 + fr; const size_t row = (size_t)chunk * 64 + 8 * w + i; const f32x4 v = acc[i][nt];
;             *(u32x2*)(YG + row * 512 + g * 16 + kg * 4) = (u32x2){pk2(gelu_tanh(v.x), gelu_tanh(v.y)), pk2(gelu_tanh(v.z), gelu_tanh(v.w))}; }
	v_mfma_f32_16x16x32_bf16 v[44:47], v[226:229], v[108:111], v[166:169]
	v_mul_f32_e64 v92, v92, v98
	v_mul_f32_e64 v93, v93, v99
	v_cvt_pk_bf16_f32 v100, v92, v93
	v_mul_f32_e32 v92, 0x3d372713, v94
	v_mul_f32_e32 v93, 0x3d372713, v95
	v_mul_f32_e32 v92, v94, v92
	v_mul_f32_e32 v93, v95, v93
	v_fma_f32 v92, v94, v92, v94
	v_fma_f32 v93, v95, v93, v95
	v_mul_f32_e32 v92, 0x3f4c422a, v92
	v_mul_f32_e32 v93, 0x3f4c422a, v93
	v_add_f32_e32 v92, v92, v92
	v_add_f32_e32 v93, v93, v93
	v_mul_f32_e32 v92, 0xbfb8aa3b, v92
	v_mul_f32_e32 v93, 0xbfb8aa3b, v93
	v_mfma_f32_16x16x32_bf16 v[40:43], v[226:229], v[112:115], v[170:173]
	v_exp_f32_e32 v92, v92
	v_exp_f32_e32 v93, v93
	v_add_f32_e32 v92, 1.0, v92
	v_mfma_f32_16x16x32_bf16 v[32:35], v[226:229], v[116:119], v[174:177]
	v_mov_b32 v96, 0
	v_add_f32_e32 v93, 1.0, v93
	v_add_u32_e32 v96, s79, v96
	ds_read_b32 v97, v96 offset:280
	ds_read_b32 v96, v96 offset:284
	v_rcp_f32_e32 v92, v92
	v_rcp_f32_e32 v93, v93
	s_waitcnt vmcnt(0)
	v_mfma_f32_16x16x32_bf16 v[24:27], v[230:233], v[108:111], v[178:181]
	s_waitcnt lgkmcnt(1)
	v_readfirstlane_b32 s4, v97
	s_waitcnt lgkmcnt(0)
	v_readfirstlane_b32 s5, v96
	s_add_u32 s0, s4, s0
	s_addc_u32 s1, s5, s1
	v_lshl_add_u64 v[96:97], s[0:1], 0, v[208:209]
	v_pk_mul_f32 v[92:93], v[94:95], v[92:93]
	v_lshlrev_b64 v[94:95], 16, v[130:131]
	v_lshl_add_u64 v[98:99], v[96:97], 0, v[94:95]
	v_cvt_pk_bf16_f32 v101, v92, v93
	v_lshlrev_b64 v[92:93], 10, v[128:129]
	v_lshl_add_u64 v[94:95], v[98:99], 0, s[28:29]
	v_lshl_add_u64 v[96:97], v[94:95], 0, v[92:93]
	global_store_dwordx2 v[96:97], v[100:101], off
	v_mul_f32_e32 v100, 0x3d372713, v88
	v_mul_f32_e32 v101, 0x3d372713, v89
	v_mul_f32_e32 v100, v88, v100
	v_mul_f32_e32 v101, v89, v101
	v_fma_f32 v100, v88, v100, v88
	v_fma_f32 v101, v89, v101, v89
	v_mul_f32_e32 v100, 0x3f4c422a, v100
	v_mul_f32_e32 v101, 0x3f4c422a, v101
	v_add_f32_e32 v100, v100, v100
	v_add_f32_e32 v101, v101, v101
	v_mul_f32_e32 v100, 0xbfb8aa3b, v100
	v_mul_f32_e32 v101, 0xbfb8aa3b, v101
	v_exp_f32_e32 v100, v100
	v_exp_f32_e32 v101, v101
	s_mov_b64 s[0:1], 0x14b00000
	v_mfma_f32_16x16x32_bf16 v[16:19], v[230:233], v[112:115], v[182:185]
	v_add_f32_e32 v100, 1.0, v100
	v_add_f32_e32 v101, 1.0, v101
	v_rcp_f32_e32 v100, v100
	v_rcp_f32_e32 v101, v101
	v_mfma_f32_16x16x32_bf16 v[8:11], v[230:233], v[116:119], v[186:189]
	s_add_i32 s8, s8, s9
	v_pk_mul_f32 v[88:89], v[88:89], v[100:101]
	s_nop 0
	v_cvt_pk_bf16_f32 v100, v88, v89
	v_mul_f32_e32 v88, 0x3d372713, v90
	v_mul_f32_e32 v89, 0x3d372713, v91
	v_mul_f32_e32 v88, v90, v88
	v_mul_f32_e32 v89, v91, v89
	v_fma_f32 v88, v90, v88, v90
	v_fma_f32 v89, v91, v89, v91
	v_mul_f32_e32 v88, 0x3f4c422a, v88
	v_mul_f32_e32 v89, 0x3f4c422a, v89
	v_add_f32_e32 v88, v88, v88
	v_add_f32_e32 v89, v89, v89
	v_mul_f32_e32 v88, 0xbfb8aa3b, v88
	v_mul_f32_e32 v89, 0xbfb8aa3b, v89
	v_exp_f32_e32 v88, v88
	v_exp_f32_e32 v89, v89
	v_mfma_f32_16x16x32_bf16 v[0:3], v[214:217], v[116:119], v[104:107]
	v_add_f32_e32 v88, 1.0, v88
	v_add_f32_e32 v89, 1.0, v89
	v_rcp_f32_e32 v88, v88
	v_rcp_f32_e32 v89, v89
	s_nop 0
	v_pk_mul_f32 v[88:89], v[90:91], v[88:89]
	s_nop 0
	v_cvt_pk_bf16_f32 v101, v88, v89
	v_lshl_add_u64 v[88:89], v[98:99], 0, s[0:1]
	v_lshl_add_u64 v[90:91], v[88:89], 0, v[92:93]
	global_store_dwordx2 v[90:91], v[100:101], off
	v_mul_f32_e32 v100, 0x3d372713, v84
	v_mul_f32_e32 v101, 0x3d372713, v85
	v_mul_f32_e32 v100, v84, v100
	v_mul_f32_e32 v101, v85, v101
	v_fma_f32 v100, v84, v100, v84
	v_fma_f32 v101, v85, v101, v85
	v_mul_f32_e32 v100, 0x3f4c422a, v100
	v_mul_f32_e32 v101, 0x3f4c422a, v101
	v_add_f32_e32 v100, v100, v100
	v_add_f32_e32 v101, v101, v101
	v_mul_f32_e32 v100, 0xbfb8aa3b, v100
	v_mul_f32_e32 v101, 0xbfb8aa3b, v101
	v_exp_f32_e32 v100, v100
	v_exp_f32_e32 v101, v101
	s_mov_b64 s[0:1], 0x14c00000
	v_add_f32_e32 v100, 1.0, v100
	v_add_f32_e32 v101, 1.0, v101
	v_rcp_f32_e32 v100, v100
	v_rcp_f32_e32 v101, v101
	s_nop 0
	v_pk_mul_f32 v[84:85], v[84:85], v[100:101]
	s_nop 0
	v_cvt_pk_bf16_f32 v100, v84, v85
	v_mul_f32_e32 v84, 0x3d372713, v86
	v_mul_f32_e32 v85, 0x3d372713, v87
	v_mul_f32_e32 v84, v86, v84
	v_mul_f32_e32 v85, v87, v85
	v_fma_f32 v84, v86, v84, v86
	v_fma_f32 v85, v87, v85, v87
	v_mul_f32_e32 v84, 0x3f4c422a, v84
	v_mul_f32_e32 v85, 0x3f4c422a, v85
	v_add_f32_e32 v84, v84, v84
	v_add_f32_e32 v85, v85, v85
	v_mul_f32_e32 v84, 0xbfb8aa3b, v84
	v_mul_f32_e32 v85, 0xbfb8aa3b, v85
	v_exp_f32_e32 v84, v84
	v_exp_f32_e32 v85, v85
	v_add_f32_e32 v84, 1.0, v84
	v_add_f32_e32 v85, 1.0, v85
	v_rcp_f32_e32 v84, v84
	v_rcp_f32_e32 v85, v85
	s_nop 0
	v_pk_mul_f32 v[84:85], v[86:87], v[84:85]
	s_nop 0
	v_cvt_pk_bf16_f32 v101, v84, v85
	v_lshl_add_u64 v[84:85], v[98:99], 0, s[0:1]
	v_mul_f32_e32 v98, 0x3d372713, v80
	v_mul_f32_e32 v99, 0x3d372713, v81
	v_mul_f32_e32 v98, v80, v98
	v_mul_f32_e32 v99, v81, v99
	v_fma_f32 v98, v80, v98, v80
	v_fma_f32 v99, v81, v99, v81
	v_mul_f32_e32 v98, 0x3f4c422a, v98
	v_mul_f32_e32 v99, 0x3f4c422a, v99
	v_add_f32_e32 v98, v98, v98
	v_add_f32_e32 v99, v99, v99
	v_mul_f32_e32 v98, 0xbfb8aa3b, v98
	v_mul_f32_e32 v99, 0xbfb8aa3b, v99
	v_exp_f32_e32 v98, v98
	v_exp_f32_e32 v99, v99
	v_lshl_add_u64 v[86:87], v[84:85], 0, v[92:93]
	global_store_dwordx2 v[86:87], v[100:101], off
	v_add_f32_e32 v98, 1.0, v98
	v_add_f32_e32 v99, 1.0, v99
	v_rcp_f32_e32 v98, v98
	v_rcp_f32_e32 v99, v99
	s_nop 0
	v_pk_mul_f32 v[80:81], v[80:81], v[98:99]
	s_nop 0
	v_cvt_pk_bf16_f32 v80, v80, v81
	v_mul_f32_e32 v81, 0x3d372713, v82
	v_mul_f32_e32 v81, v82, v81
	v_fma_f32 v81, v82, v81, v82
	v_mul_f32_e32 v81, 0x3f4c422a, v81
	v_add_f32_e32 v81, v81, v81
	v_mul_f32_e32 v81, 0xbfb8aa3b, v81
; __device__ __forceinline__ unsigned pk2(float lo, float hi) { const f32x2 v = {lo, hi}; return __builtin_bit_cast(unsigned, __builtin_convertvector(v, bf16x2_t)); }
; __device__ __forceinline__ float gelu_tanh(float x) { const float y = 0.7978845608028654f * (x + 0.044715f * x * x * x); return x * sigmoidf_(2.f * y); }
; __device__ __forceinline__ float sigmoidf_(float x) { return __builtin_amdgcn_rcpf(1.f + __builtin_amdgcn_exp2f(-x * LOG2E)); }
; __device__ __forceinline__ void s5_out_unit(const PA& a, int unit, LAS unsigned char* lds, int tid_) {
;     ...
;     for (int i = 0; i < 8; ++i)
; #pragma unroll
;         for (int nt = 0; nt < 3; ++nt) { const int chunk = nb * 48 + nt * 16 + fr; const size_t row = (size_t)chunk * 64 + 8 * w + i; const f32x4 v = acc[i][nt];
;             *(u32x2*)(YG + row * 512 + g * 16 + kg * 4) = (u32x2){pk2(gelu_tanh(v.x), gelu_tanh(v.y)), pk2(gelu_tanh(v.z), gelu_tanh(v.w))}; }
	v_exp_f32_e32 v81, v81
	s_nop 0
	v_add_f32_e32 v81, 1.0, v81
	v_rcp_f32_e32 v98, v81
	v_mul_f32_e32 v81, 0x3d372713, v83
	v_mul_f32_e32 v81, v83, v81
	v_fma_f32 v81, v83, v81, v83
	v_mul_f32_e32 v81, 0x3f4c422a, v81
	v_add_f32_e32 v81, v81, v81
	v_mul_f32_e32 v81, 0xbfb8aa3b, v81
	v_exp_f32_e32 v81, v81
	s_nop 0
	v_add_f32_e32 v81, 1.0, v81
	v_rcp_f32_e32 v99, v81
	s_nop 0
	v_pk_mul_f32 v[82:83], v[82:83], v[98:99]
	s_nop 0
	v_cvt_pk_bf16_f32 v81, v82, v83
	global_store_dwordx2 v[96:97], v[80:81], off offset:1024
	v_mul_f32_e32 v80, 0x3d372713, v76
	v_mul_f32_e32 v81, 0x3d372713, v77
	v_mul_f32_e32 v80, v76, v80
	v_mul_f32_e32 v81, v77, v81
	v_fma_f32 v80, v76, v80, v76
	v_fma_f32 v81, v77, v81, v77
	v_mul_f32_e32 v80, 0x3f4c422a, v80
	v_mul_f32_e32 v81, 0x3f4c422a, v81
	v_add_f32_e32 v80, v80, v80
	v_add_f32_e32 v81, v81, v81
	v_mul_f32_e32 v80, 0xbfb8aa3b, v80
	v_mul_f32_e32 v81, 0xbfb8aa3b, v81
	v_exp_f32_e32 v80, v80
	v_exp_f32_e32 v81, v81
	v_add_f32_e32 v80, 1.0, v80
	v_add_f32_e32 v81, 1.0, v81
	v_rcp_f32_e32 v80, v80
	v_rcp_f32_e32 v81, v81
	s_nop 0
	v_pk_mul_f32 v[76:77], v[76:77], v[80:81]
	s_nop 0
	v_cvt_pk_bf16_f32 v76, v76, v77
	v_mul_f32_e32 v77, 0x3d372713, v78
	v_mul_f32_e32 v77, v78, v77
	v_fma_f32 v77, v78, v77, v78
	v_mul_f32_e32 v77, 0x3f4c422a, v77
	v_add_f32_e32 v77, v77, v77
	v_mul_f32_e32 v77, 0xbfb8aa3b, v77
	v_exp_f32_e32 v77, v77
	s_nop 0
	v_add_f32_e32 v77, 1.0, v77
	v_rcp_f32_e32 v80, v77
	v_mul_f32_e32 v77, 0x3d372713, v79
	v_mul_f32_e32 v77, v79, v77
	v_fma_f32 v77, v79, v77, v79
	v_mul_f32_e32 v77, 0x3f4c422a, v77
	v_add_f32_e32 v77, v77, v77
	v_mul_f32_e32 v77, 0xbfb8aa3b, v77
	v_exp_f32_e32 v77, v77
	s_nop 0
	v_add_f32_e32 v77, 1.0, v77
	v_rcp_f32_e32 v81, v77
	s_nop 0
	v_pk_mul_f32 v[78:79], v[78:79], v[80:81]
	s_nop 0
	v_cvt_pk_bf16_f32 v77, v78, v79
	global_store_dwordx2 v[90:91], v[76:77], off offset:1024
	v_mul_f32_e32 v76, 0x3d372713, v72
	v_mul_f32_e32 v77, 0x3d372713, v73
	v_mul_f32_e32 v76, v72, v76
	v_mul_f32_e32 v77, v73, v77
	v_fma_f32 v76, v72, v76, v72
	v_fma_f32 v77, v73, v77, v73
	v_mul_f32_e32 v76, 0x3f4c422a, v76
	v_mul_f32_e32 v77, 0x3f4c422a, v77
	v_add_f32_e32 v76, v76, v76
	v_add_f32_e32 v77, v77, v77
	v_mul_f32_e32 v76, 0xbfb8aa3b, v76
	v_mul_f32_e32 v77, 0xbfb8aa3b, v77
	v_exp_f32_e32 v76, v76
	v_exp_f32_e32 v77, v77
	v_add_f32_e32 v76, 1.0, v76
	v_add_f32_e32 v77, 1.0, v77
	v_rcp_f32_e32 v76, v76
	v_rcp_f32_e32 v77, v77
	s_nop 0
	v_pk_mul_f32 v[72:73], v[72:73], v[76:77]
	s_nop 0
	v_cvt_pk_bf16_f32 v72, v72, v73
	v_mul_f32_e32 v73, 0x3d372713, v74
	v_mul_f32_e32 v73, v74, v73
	v_fma_f32 v73, v74, v73, v74
	v_mul_f32_e32 v73, 0x3f4c422a, v73
	v_add_f32_e32 v73, v73, v73
	v_mul_f32_e32 v73, 0xbfb8aa3b, v73
	v_exp_f32_e32 v73, v73
	s_nop 0
	v_add_f32_e32 v73, 1.0, v73
	v_rcp_f32_e32 v76, v73
	v_mul_f32_e32 v73, 0x3d372713, v75
	v_mul_f32_e32 v73, v75, v73
	v_fma_f32 v73, v75, v73, v75
	v_mul_f32_e32 v73, 0x3f4c422a, v73
	v_add_f32_e32 v73, v73, v73
	v_mul_f32_e32 v73, 0xbfb8aa3b, v73
	v_exp_f32_e32 v73, v73
	s_nop 0
	v_add_f32_e32 v73, 1.0, v73
	v_rcp_f32_e32 v77, v73
	s_nop 0
	v_pk_mul_f32 v[74:75], v[74:75], v[76:77]
	s_nop 0
	v_cvt_pk_bf16_f32 v73, v74, v75
	global_store_dwordx2 v[86:87], v[72:73], off offset:1024
	v_mul_f32_e32 v72, 0x3d372713, v68
	v_mul_f32_e32 v73, 0x3d372713, v69
	v_mul_f32_e32 v72, v68, v72
	v_mul_f32_e32 v73, v69, v73
	v_fma_f32 v72, v68, v72, v68
	v_fma_f32 v73, v69, v73, v69
	v_mul_f32_e32 v72, 0x3f4c422a, v72
	v_mul_f32_e32 v73, 0x3f4c422a, v73
	v_add_f32_e32 v72, v72, v72
	v_add_f32_e32 v73, v73, v73
	v_mul_f32_e32 v72, 0xbfb8aa3b, v72
	v_mul_f32_e32 v73, 0xbfb8aa3b, v73
	v_exp_f32_e32 v72, v72
	v_exp_f32_e32 v73, v73
	v_add_f32_e32 v72, 1.0, v72
	v_add_f32_e32 v73, 1.0, v73
	v_rcp_f32_e32 v72, v72
	v_rcp_f32_e32 v73, v73
	s_nop 0
	v_pk_mul_f32 v[68:69], v[68:69], v[72:73]
	s_nop 0
	v_cvt_pk_bf16_f32 v68, v68, v69
	v_mul_f32_e32 v69, 0x3d372713, v70
	v_mul_f32_e32 v69, v70, v69
	v_fma_f32 v69, v70, v69, v70
	v_mul_f32_e32 v69, 0x3f4c422a, v69
	v_add_f32_e32 v69, v69, v69
	v_mul_f32_e32 v69, 0xbfb8aa3b, v69
	v_exp_f32_e32 v69, v69
	s_nop 0
	v_add_f32_e32 v69, 1.0, v69
	v_rcp_f32_e32 v72, v69
	v_mul_f32_e32 v69, 0x3d372713, v71
	v_mul_f32_e32 v69, v71, v69
	v_fma_f32 v69, v71, v69, v71
	v_mul_f32_e32 v69, 0x3f4c422a, v69
	v_add_f32_e32 v69, v69, v69
	v_mul_f32_e32 v69, 0xbfb8aa3b, v69
	v_exp_f32_e32 v69, v69
	s_nop 0
	v_add_f32_e32 v69, 1.0, v69
	v_rcp_f32_e32 v73, v69
	s_nop 0
	v_pk_mul_f32 v[70:71], v[70:71], v[72:73]
	s_nop 0
	v_cvt_pk_bf16_f32 v69, v70, v71
	global_store_dwordx2 v[96:97], v[68:69], off offset:2048
	v_mul_f32_e32 v68, 0x3d372713, v64
	v_mul_f32_e32 v69, 0x3d372713, v65
	v_mul_f32_e32 v68, v64, v68
	v_mul_f32_e32 v69, v65, v69
	v_fma_f32 v68, v64, v68, v64
	v_fma_f32 v69, v65, v69, v65
	v_mul_f32_e32 v68, 0x3f4c422a, v68
	v_mul_f32_e32 v69, 0x3f4c422a, v69
	v_add_f32_e32 v68, v68, v68
	v_add_f32_e32 v69, v69, v69
	v_mul_f32_e32 v68, 0xbfb8aa3b, v68
	v_mul_f32_e32 v69, 0xbfb8aa3b, v69
	v_exp_f32_e32 v68, v68
	v_exp_f32_e32 v69, v69
	v_add_f32_e32 v68, 1.0, v68
	v_add_f32_e32 v69, 1.0, v69
	v_rcp_f32_e32 v68, v68
	v_rcp_f32_e32 v69, v69
	s_nop 0
	v_pk_mul_f32 v[64:65], v[64:65], v[68:69]
	s_nop 0
	v_cvt_pk_bf16_f32 v64, v64, v65
	v_mul_f32_e32 v65, 0x3d372713, v66
	v_mul_f32_e32 v65, v66, v65
	v_fma_f32 v65, v66, v65, v66
	v_mul_f32_e32 v65, 0x3f4c422a, v65
	v_add_f32_e32 v65, v65, v65
	v_mul_f32_e32 v65, 0xbfb8aa3b, v65
	v_exp_f32_e32 v65, v65
	s_nop 0
	v_add_f32_e32 v65, 1.0, v65
	v_rcp_f32_e32 v68, v65
	v_mul_f32_e32 v65, 0x3d372713, v67
	v_mul_f32_e32 v65, v67, v65
	v_fma_f32 v65, v67, v65, v67
	v_mul_f32_e32 v65, 0x3f4c422a, v65
; __device__ __forceinline__ unsigned pk2(float lo, float hi) { const f32x2 v = {lo, hi}; return __builtin_bit_cast(unsigned, __builtin_convertvector(v, bf16x2_t)); }
; __device__ __forceinline__ float gelu_tanh(float x) { const float y = 0.7978845608028654f * (x + 0.044715f * x * x * x); return x * sigmoidf_(2.f * y); }
; __device__ __forceinline__ float sigmoidf_(float x) { return __builtin_amdgcn_rcpf(1.f + __builtin_amdgcn_exp2f(-x * LOG2E)); }
; __device__ __forceinline__ void s5_out_unit(const PA& a, int unit, LAS unsigned char* lds, int tid_) {
;     ...
;     for (int i = 0; i < 8; ++i)
; #pragma unroll
;         for (int nt = 0; nt < 3; ++nt) { const int chunk = nb * 48 + nt * 16 + fr; const size_t row = (size_t)chunk * 64 + 8 * w + i; const f32x4 v = acc[i][nt];
;             *(u32x2*)(YG + row * 512 + g * 16 + kg * 4) = (u32x2){pk2(gelu_tanh(v.x), gelu_tanh(v.y)), pk2(gelu_tanh(v.z), gelu_tanh(v.w))}; }
	v_add_f32_e32 v65, v65, v65
	v_mul_f32_e32 v65, 0xbfb8aa3b, v65
	v_exp_f32_e32 v65, v65
	s_nop 0
	v_add_f32_e32 v65, 1.0, v65
	v_rcp_f32_e32 v69, v65
	s_nop 0
	v_pk_mul_f32 v[66:67], v[66:67], v[68:69]
	s_nop 0
	v_cvt_pk_bf16_f32 v65, v66, v67
	global_store_dwordx2 v[90:91], v[64:65], off offset:2048
	v_mul_f32_e32 v64, 0x3d372713, v60
	v_mul_f32_e32 v65, 0x3d372713, v61
	v_mul_f32_e32 v64, v60, v64
	v_mul_f32_e32 v65, v61, v65
	v_fma_f32 v64, v60, v64, v60
	v_fma_f32 v65, v61, v65, v61
	v_mul_f32_e32 v64, 0x3f4c422a, v64
	v_mul_f32_e32 v65, 0x3f4c422a, v65
	v_add_f32_e32 v64, v64, v64
	v_add_f32_e32 v65, v65, v65
	v_mul_f32_e32 v64, 0xbfb8aa3b, v64
	v_mul_f32_e32 v65, 0xbfb8aa3b, v65
	v_exp_f32_e32 v64, v64
	v_exp_f32_e32 v65, v65
	v_add_f32_e32 v64, 1.0, v64
	v_add_f32_e32 v65, 1.0, v65
	v_rcp_f32_e32 v64, v64
	v_rcp_f32_e32 v65, v65
	s_nop 0
	v_pk_mul_f32 v[60:61], v[60:61], v[64:65]
	s_nop 0
	v_cvt_pk_bf16_f32 v60, v60, v61
	v_mul_f32_e32 v61, 0x3d372713, v62
	v_mul_f32_e32 v61, v62, v61
	v_fma_f32 v61, v62, v61, v62
	v_mul_f32_e32 v61, 0x3f4c422a, v61
	v_add_f32_e32 v61, v61, v61
	v_mul_f32_e32 v61, 0xbfb8aa3b, v61
	v_exp_f32_e32 v61, v61
	s_nop 0
	v_add_f32_e32 v61, 1.0, v61
	v_rcp_f32_e32 v64, v61
	v_mul_f32_e32 v61, 0x3d372713, v63
	v_mul_f32_e32 v61, v63, v61
	v_fma_f32 v61, v63, v61, v63
	v_mul_f32_e32 v61, 0x3f4c422a, v61
	v_add_f32_e32 v61, v61, v61
	v_mul_f32_e32 v61, 0xbfb8aa3b, v61
	v_exp_f32_e32 v61, v61
	s_nop 0
	v_add_f32_e32 v61, 1.0, v61
	v_rcp_f32_e32 v65, v61
	s_nop 0
	v_pk_mul_f32 v[62:63], v[62:63], v[64:65]
	s_nop 0
	v_cvt_pk_bf16_f32 v61, v62, v63
	global_store_dwordx2 v[86:87], v[60:61], off offset:2048
	v_mul_f32_e32 v60, 0x3d372713, v56
	v_mul_f32_e32 v61, 0x3d372713, v57
	v_mul_f32_e32 v60, v56, v60
	v_mul_f32_e32 v61, v57, v61
	v_fma_f32 v60, v56, v60, v56
	v_fma_f32 v61, v57, v61, v57
	v_mul_f32_e32 v60, 0x3f4c422a, v60
	v_mul_f32_e32 v61, 0x3f4c422a, v61
	v_add_f32_e32 v60, v60, v60
	v_add_f32_e32 v61, v61, v61
	v_mul_f32_e32 v60, 0xbfb8aa3b, v60
	v_mul_f32_e32 v61, 0xbfb8aa3b, v61
	v_exp_f32_e32 v60, v60
	v_exp_f32_e32 v61, v61
	v_add_f32_e32 v60, 1.0, v60
	v_add_f32_e32 v61, 1.0, v61
	v_rcp_f32_e32 v60, v60
	v_rcp_f32_e32 v61, v61
	s_nop 0
	v_pk_mul_f32 v[56:57], v[56:57], v[60:61]
	s_nop 0
	v_cvt_pk_bf16_f32 v56, v56, v57
	v_mul_f32_e32 v57, 0x3d372713, v58
	v_mul_f32_e32 v57, v58, v57
	v_fma_f32 v57, v58, v57, v58
	v_mul_f32_e32 v57, 0x3f4c422a, v57
	v_add_f32_e32 v57, v57, v57
	v_mul_f32_e32 v57, 0xbfb8aa3b, v57
	v_exp_f32_e32 v57, v57
	s_nop 0
	v_add_f32_e32 v57, 1.0, v57
	v_rcp_f32_e32 v60, v57
	v_mul_f32_e32 v57, 0x3d372713, v59
	v_mul_f32_e32 v57, v59, v57
	v_fma_f32 v57, v59, v57, v59
	v_mul_f32_e32 v57, 0x3f4c422a, v57
	v_add_f32_e32 v57, v57, v57
	v_mul_f32_e32 v57, 0xbfb8aa3b, v57
	v_exp_f32_e32 v57, v57
	s_nop 0
	v_add_f32_e32 v57, 1.0, v57
	v_rcp_f32_e32 v61, v57
	s_nop 0
	v_pk_mul_f32 v[58:59], v[58:59], v[60:61]
	s_nop 0
	v_cvt_pk_bf16_f32 v57, v58, v59
	global_store_dwordx2 v[96:97], v[56:57], off offset:3072
	v_mul_f32_e32 v56, 0x3d372713, v52
	v_mul_f32_e32 v57, 0x3d372713, v53
	v_mul_f32_e32 v56, v52, v56
	v_mul_f32_e32 v57, v53, v57
	v_fma_f32 v56, v52, v56, v52
	v_fma_f32 v57, v53, v57, v53
	v_mul_f32_e32 v56, 0x3f4c422a, v56
	v_mul_f32_e32 v57, 0x3f4c422a, v57
	v_add_f32_e32 v56, v56, v56
	v_add_f32_e32 v57, v57, v57
	v_mul_f32_e32 v56, 0xbfb8aa3b, v56
	v_mul_f32_e32 v57, 0xbfb8aa3b, v57
	v_exp_f32_e32 v56, v56
	v_exp_f32_e32 v57, v57
	v_add_f32_e32 v56, 1.0, v56
	v_add_f32_e32 v57, 1.0, v57
	v_rcp_f32_e32 v56, v56
	v_rcp_f32_e32 v57, v57
	s_nop 0
	v_pk_mul_f32 v[52:53], v[52:53], v[56:57]
	s_nop 0
	v_cvt_pk_bf16_f32 v52, v52, v53
	v_mul_f32_e32 v53, 0x3d372713, v54
	v_mul_f32_e32 v53, v54, v53
	v_fma_f32 v53, v54, v53, v54
	v_mul_f32_e32 v53, 0x3f4c422a, v53
	v_add_f32_e32 v53, v53, v53
	v_mul_f32_e32 v53, 0xbfb8aa3b, v53
	v_exp_f32_e32 v53, v53
	s_nop 0
	v_add_f32_e32 v53, 1.0, v53
	v_rcp_f32_e32 v56, v53
	v_mul_f32_e32 v53, 0x3d372713, v55
	v_mul_f32_e32 v53, v55, v53
	v_fma_f32 v53, v55, v53, v55
	v_mul_f32_e32 v53, 0x3f4c422a, v53
	v_add_f32_e32 v53, v53, v53
	v_mul_f32_e32 v53, 0xbfb8aa3b, v53
	v_exp_f32_e32 v53, v53
	s_nop 0
	v_add_f32_e32 v53, 1.0, v53
	v_rcp_f32_e32 v57, v53
	s_nop 0
	v_pk_mul_f32 v[54:55], v[54:55], v[56:57]
	s_nop 0
	v_cvt_pk_bf16_f32 v53, v54, v55
	global_store_dwordx2 v[90:91], v[52:53], off offset:3072
	v_mul_f32_e32 v52, 0x3d372713, v48
	v_mul_f32_e32 v53, 0x3d372713, v49
	v_mul_f32_e32 v52, v48, v52
	v_mul_f32_e32 v53, v49, v53
	v_fma_f32 v52, v48, v52, v48
	v_fma_f32 v53, v49, v53, v49
	v_mul_f32_e32 v52, 0x3f4c422a, v52
	v_mul_f32_e32 v53, 0x3f4c422a, v53
	v_add_f32_e32 v52, v52, v52
	v_add_f32_e32 v53, v53, v53
	v_mul_f32_e32 v52, 0xbfb8aa3b, v52
	v_mul_f32_e32 v53, 0xbfb8aa3b, v53
	v_exp_f32_e32 v52, v52
	v_exp_f32_e32 v53, v53
	v_add_f32_e32 v52, 1.0, v52
	v_add_f32_e32 v53, 1.0, v53
	v_rcp_f32_e32 v52, v52
	v_rcp_f32_e32 v53, v53
	s_nop 0
	v_pk_mul_f32 v[48:49], v[48:49], v[52:53]
	s_nop 0
	v_cvt_pk_bf16_f32 v48, v48, v49
	v_mul_f32_e32 v49, 0x3d372713, v50
	v_mul_f32_e32 v49, v50, v49
	v_fma_f32 v49, v50, v49, v50
	v_mul_f32_e32 v49, 0x3f4c422a, v49
	v_add_f32_e32 v49, v49, v49
	v_mul_f32_e32 v49, 0xbfb8aa3b, v49
	v_exp_f32_e32 v49, v49
	s_nop 0
	v_add_f32_e32 v49, 1.0, v49
	v_rcp_f32_e32 v52, v49
	v_mul_f32_e32 v49, 0x3d372713, v51
	v_mul_f32_e32 v49, v51, v49
	v_fma_f32 v49, v51, v49, v51
	v_mul_f32_e32 v49, 0x3f4c422a, v49
	v_add_f32_e32 v49, v49, v49
	v_mul_f32_e32 v49, 0xbfb8aa3b, v49
	v_exp_f32_e32 v49, v49
	s_nop 0
	v_add_f32_e32 v49, 1.0, v49
	v_rcp_f32_e32 v53, v49
	s_nop 0
	v_pk_mul_f32 v[50:51], v[50:51], v[52:53]
	s_nop 0
; __device__ __forceinline__ unsigned pk2(float lo, float hi) { const f32x2 v = {lo, hi}; return __builtin_bit_cast(unsigned, __builtin_convertvector(v, bf16x2_t)); }
; __device__ __forceinline__ float gelu_tanh(float x) { const float y = 0.7978845608028654f * (x + 0.044715f * x * x * x); return x * sigmoidf_(2.f * y); }
; __device__ __forceinline__ float sigmoidf_(float x) { return __builtin_amdgcn_rcpf(1.f + __builtin_amdgcn_exp2f(-x * LOG2E)); }
; __device__ __forceinline__ void s5_out_unit(const PA& a, int unit, LAS unsigned char* lds, int tid_) {
;     ...
;     for (int i = 0; i < 8; ++i)
; #pragma unroll
;         for (int nt = 0; nt < 3; ++nt) { const int chunk = nb * 48 + nt * 16 + fr; const size_t row = (size_t)chunk * 64 + 8 * w + i; const f32x4 v = acc[i][nt];
;             *(u32x2*)(YG + row * 512 + g * 16 + kg * 4) = (u32x2){pk2(gelu_tanh(v.x), gelu_tanh(v.y)), pk2(gelu_tanh(v.z), gelu_tanh(v.w))}; }
	v_cvt_pk_bf16_f32 v49, v50, v51
	global_store_dwordx2 v[86:87], v[48:49], off offset:3072
	v_mul_f32_e32 v48, 0x3d372713, v44
	v_mul_f32_e32 v49, 0x3d372713, v45
	v_mul_f32_e32 v48, v44, v48
	v_mul_f32_e32 v49, v45, v49
	v_fma_f32 v48, v44, v48, v44
	v_fma_f32 v49, v45, v49, v45
	v_mul_f32_e32 v48, 0x3f4c422a, v48
	v_mul_f32_e32 v49, 0x3f4c422a, v49
	v_add_f32_e32 v48, v48, v48
	v_add_f32_e32 v49, v49, v49
	v_mul_f32_e32 v48, 0xbfb8aa3b, v48
	v_mul_f32_e32 v49, 0xbfb8aa3b, v49
	v_exp_f32_e32 v48, v48
	v_exp_f32_e32 v49, v49
	v_add_f32_e32 v48, 1.0, v48
	v_add_f32_e32 v49, 1.0, v49
	v_rcp_f32_e32 v48, v48
	v_rcp_f32_e32 v49, v49
	s_nop 0
	v_pk_mul_f32 v[44:45], v[44:45], v[48:49]
	s_nop 0
	v_cvt_pk_bf16_f32 v44, v44, v45
	v_mul_f32_e32 v45, 0x3d372713, v46
	v_mul_f32_e32 v45, v46, v45
	v_fma_f32 v45, v46, v45, v46
	v_mul_f32_e32 v45, 0x3f4c422a, v45
	v_add_f32_e32 v45, v45, v45
	v_mul_f32_e32 v45, 0xbfb8aa3b, v45
	v_exp_f32_e32 v45, v45
	s_nop 0
	v_add_f32_e32 v45, 1.0, v45
	v_rcp_f32_e32 v48, v45
	v_mul_f32_e32 v45, 0x3d372713, v47
	v_mul_f32_e32 v45, v47, v45
	v_fma_f32 v45, v47, v45, v47
	v_mul_f32_e32 v45, 0x3f4c422a, v45
	v_add_f32_e32 v45, v45, v45
	v_mul_f32_e32 v45, 0xbfb8aa3b, v45
	v_exp_f32_e32 v45, v45
	s_nop 0
	v_add_f32_e32 v45, 1.0, v45
	v_rcp_f32_e32 v49, v45
	s_nop 0
	v_pk_mul_f32 v[46:47], v[46:47], v[48:49]
	s_nop 0
	v_cvt_pk_bf16_f32 v45, v46, v47
	v_or_b32_e32 v46, 0x1000, v92
	v_mov_b32_e32 v47, v93
	v_lshl_add_u64 v[48:49], v[94:95], 0, v[46:47]
	global_store_dwordx2 v[48:49], v[44:45], off
	v_mul_f32_e32 v44, 0x3d372713, v40
	v_mul_f32_e32 v45, 0x3d372713, v41
	v_mul_f32_e32 v44, v40, v44
	v_mul_f32_e32 v45, v41, v45
	v_fma_f32 v44, v40, v44, v40
	v_fma_f32 v45, v41, v45, v41
	v_mul_f32_e32 v44, 0x3f4c422a, v44
	v_mul_f32_e32 v45, 0x3f4c422a, v45
	v_add_f32_e32 v44, v44, v44
	v_add_f32_e32 v45, v45, v45
	v_mul_f32_e32 v44, 0xbfb8aa3b, v44
	v_mul_f32_e32 v45, 0xbfb8aa3b, v45
	v_exp_f32_e32 v44, v44
	v_exp_f32_e32 v45, v45
	v_add_f32_e32 v44, 1.0, v44
	v_add_f32_e32 v45, 1.0, v45
	v_rcp_f32_e32 v44, v44
	v_rcp_f32_e32 v45, v45
	s_nop 0
	v_pk_mul_f32 v[40:41], v[40:41], v[44:45]
	s_nop 0
	v_cvt_pk_bf16_f32 v40, v40, v41
	v_mul_f32_e32 v41, 0x3d372713, v42
	v_mul_f32_e32 v41, v42, v41
	v_fma_f32 v41, v42, v41, v42
	v_mul_f32_e32 v41, 0x3f4c422a, v41
	v_add_f32_e32 v41, v41, v41
	v_mul_f32_e32 v41, 0xbfb8aa3b, v41
	v_exp_f32_e32 v41, v41
	s_nop 0
	v_add_f32_e32 v41, 1.0, v41
	v_rcp_f32_e32 v44, v41
	v_mul_f32_e32 v41, 0x3d372713, v43
	v_mul_f32_e32 v41, v43, v41
	v_fma_f32 v41, v43, v41, v43
	v_mul_f32_e32 v41, 0x3f4c422a, v41
	v_add_f32_e32 v41, v41, v41
	v_mul_f32_e32 v41, 0xbfb8aa3b, v41
	v_exp_f32_e32 v41, v41
	s_nop 0
	v_add_f32_e32 v41, 1.0, v41
	v_rcp_f32_e32 v45, v41
	s_nop 0
	v_pk_mul_f32 v[42:43], v[42:43], v[44:45]
	s_nop 0
	v_cvt_pk_bf16_f32 v41, v42, v43
	v_lshl_add_u64 v[42:43], v[88:89], 0, v[46:47]
	global_store_dwordx2 v[42:43], v[40:41], off
	v_mul_f32_e32 v40, 0x3d372713, v32
	v_mul_f32_e32 v41, 0x3d372713, v33
	v_mul_f32_e32 v40, v32, v40
	v_mul_f32_e32 v41, v33, v41
	v_fma_f32 v40, v32, v40, v32
	v_fma_f32 v41, v33, v41, v33
	v_mul_f32_e32 v40, 0x3f4c422a, v40
	v_mul_f32_e32 v41, 0x3f4c422a, v41
	v_add_f32_e32 v40, v40, v40
	v_add_f32_e32 v41, v41, v41
	v_mul_f32_e32 v40, 0xbfb8aa3b, v40
	v_mul_f32_e32 v41, 0xbfb8aa3b, v41
	v_exp_f32_e32 v40, v40
	v_exp_f32_e32 v41, v41
	v_add_f32_e32 v40, 1.0, v40
	v_add_f32_e32 v41, 1.0, v41
	v_rcp_f32_e32 v40, v40
	v_rcp_f32_e32 v41, v41
	s_nop 0
	v_pk_mul_f32 v[32:33], v[32:33], v[40:41]
	s_nop 0
	v_cvt_pk_bf16_f32 v32, v32, v33
	v_mul_f32_e32 v33, 0x3d372713, v34
	v_mul_f32_e32 v33, v34, v33
	v_fma_f32 v33, v34, v33, v34
	v_mul_f32_e32 v33, 0x3f4c422a, v33
	v_add_f32_e32 v33, v33, v33
	v_mul_f32_e32 v33, 0xbfb8aa3b, v33
	v_exp_f32_e32 v33, v33
	s_nop 0
	v_add_f32_e32 v33, 1.0, v33
	v_rcp_f32_e32 v40, v33
	v_mul_f32_e32 v33, 0x3d372713, v35
	v_mul_f32_e32 v33, v35, v33
	v_fma_f32 v33, v35, v33, v35
	v_mul_f32_e32 v33, 0x3f4c422a, v33
	v_add_f32_e32 v33, v33, v33
	v_mul_f32_e32 v33, 0xbfb8aa3b, v33
	v_exp_f32_e32 v33, v33
	s_nop 0
	v_add_f32_e32 v33, 1.0, v33
	v_rcp_f32_e32 v41, v33
	s_nop 0
	v_pk_mul_f32 v[34:35], v[34:35], v[40:41]
	s_nop 0
	v_cvt_pk_bf16_f32 v33, v34, v35
	v_lshl_add_u64 v[34:35], v[84:85], 0, v[46:47]
	global_store_dwordx2 v[34:35], v[32:33], off
	v_mul_f32_e32 v32, 0x3d372713, v24
	v_mul_f32_e32 v33, 0x3d372713, v25
	v_mul_f32_e32 v32, v24, v32
	v_mul_f32_e32 v33, v25, v33
	v_fma_f32 v32, v24, v32, v24
	v_fma_f32 v33, v25, v33, v25
	v_mul_f32_e32 v32, 0x3f4c422a, v32
	v_mul_f32_e32 v33, 0x3f4c422a, v33
	v_add_f32_e32 v32, v32, v32
	v_add_f32_e32 v33, v33, v33
	v_mul_f32_e32 v32, 0xbfb8aa3b, v32
	v_mul_f32_e32 v33, 0xbfb8aa3b, v33
	v_exp_f32_e32 v32, v32
	v_exp_f32_e32 v33, v33
	v_add_f32_e32 v32, 1.0, v32
	v_add_f32_e32 v33, 1.0, v33
	v_rcp_f32_e32 v32, v32
	v_rcp_f32_e32 v33, v33
	s_nop 0
	v_pk_mul_f32 v[24:25], v[24:25], v[32:33]
	s_nop 0
	v_cvt_pk_bf16_f32 v24, v24, v25
	v_mul_f32_e32 v25, 0x3d372713, v26
	v_mul_f32_e32 v25, v26, v25
	v_fma_f32 v25, v26, v25, v26
	v_mul_f32_e32 v25, 0x3f4c422a, v25
	v_add_f32_e32 v25, v25, v25
	v_mul_f32_e32 v25, 0xbfb8aa3b, v25
	v_exp_f32_e32 v25, v25
	s_nop 0
	v_add_f32_e32 v25, 1.0, v25
	v_rcp_f32_e32 v32, v25
	v_mul_f32_e32 v25, 0x3d372713, v27
	v_mul_f32_e32 v25, v27, v25
	v_fma_f32 v25, v27, v25, v27
	v_mul_f32_e32 v25, 0x3f4c422a, v25
	v_add_f32_e32 v25, v25, v25
	v_mul_f32_e32 v25, 0xbfb8aa3b, v25
	v_exp_f32_e32 v25, v25
	s_nop 0
	v_add_f32_e32 v25, 1.0, v25
	v_rcp_f32_e32 v33, v25
	s_nop 0
	v_pk_mul_f32 v[26:27], v[26:27], v[32:33]
	s_nop 0
	v_cvt_pk_bf16_f32 v25, v26, v27
	v_or_b32_e32 v26, 0x1400, v92
; __device__ __forceinline__ unsigned pk2(float lo, float hi) { const f32x2 v = {lo, hi}; return __builtin_bit_cast(unsigned, __builtin_convertvector(v, bf16x2_t)); }
; __device__ __forceinline__ float gelu_tanh(float x) { const float y = 0.7978845608028654f * (x + 0.044715f * x * x * x); return x * sigmoidf_(2.f * y); }
; __device__ __forceinline__ float sigmoidf_(float x) { return __builtin_amdgcn_rcpf(1.f + __builtin_amdgcn_exp2f(-x * LOG2E)); }
; __device__ __forceinline__ void s5_out_unit(const PA& a, int unit, LAS unsigned char* lds, int tid_) {
;     ...
;     for (int i = 0; i < 8; ++i)
; #pragma unroll
;         for (int nt = 0; nt < 3; ++nt) { const int chunk = nb * 48 + nt * 16 + fr; const size_t row = (size_t)chunk * 64 + 8 * w + i; const f32x4 v = acc[i][nt];
;             *(u32x2*)(YG + row * 512 + g * 16 + kg * 4) = (u32x2){pk2(gelu_tanh(v.x), gelu_tanh(v.y)), pk2(gelu_tanh(v.z), gelu_tanh(v.w))}; }
	v_mov_b32_e32 v27, v93
	v_lshl_add_u64 v[32:33], v[94:95], 0, v[26:27]
	global_store_dwordx2 v[32:33], v[24:25], off
	v_mul_f32_e32 v24, 0x3d372713, v16
	v_mul_f32_e32 v25, 0x3d372713, v17
	v_mul_f32_e32 v24, v16, v24
	v_mul_f32_e32 v25, v17, v25
	v_fma_f32 v24, v16, v24, v16
	v_fma_f32 v25, v17, v25, v17
	v_mul_f32_e32 v24, 0x3f4c422a, v24
	v_mul_f32_e32 v25, 0x3f4c422a, v25
	v_add_f32_e32 v24, v24, v24
	v_add_f32_e32 v25, v25, v25
	v_mul_f32_e32 v24, 0xbfb8aa3b, v24
	v_mul_f32_e32 v25, 0xbfb8aa3b, v25
	v_exp_f32_e32 v24, v24
	v_exp_f32_e32 v25, v25
	v_add_f32_e32 v24, 1.0, v24
	v_add_f32_e32 v25, 1.0, v25
	v_rcp_f32_e32 v24, v24
	v_rcp_f32_e32 v25, v25
	s_nop 0
	v_pk_mul_f32 v[16:17], v[16:17], v[24:25]
	s_nop 0
	v_cvt_pk_bf16_f32 v16, v16, v17
	v_mul_f32_e32 v17, 0x3d372713, v18
	v_mul_f32_e32 v17, v18, v17
	v_fma_f32 v17, v18, v17, v18
	v_mul_f32_e32 v17, 0x3f4c422a, v17
	v_add_f32_e32 v17, v17, v17
	v_mul_f32_e32 v17, 0xbfb8aa3b, v17
	v_exp_f32_e32 v17, v17
	s_nop 0
	v_add_f32_e32 v17, 1.0, v17
	v_rcp_f32_e32 v24, v17
	v_mul_f32_e32 v17, 0x3d372713, v19
	v_mul_f32_e32 v17, v19, v17
	v_fma_f32 v17, v19, v17, v19
	v_mul_f32_e32 v17, 0x3f4c422a, v17
	v_add_f32_e32 v17, v17, v17
	v_mul_f32_e32 v17, 0xbfb8aa3b, v17
	v_exp_f32_e32 v17, v17
	s_nop 0
	v_add_f32_e32 v17, 1.0, v17
	v_rcp_f32_e32 v25, v17
	s_nop 0
	v_pk_mul_f32 v[18:19], v[18:19], v[24:25]
	s_nop 0
	v_cvt_pk_bf16_f32 v17, v18, v19
	v_lshl_add_u64 v[18:19], v[88:89], 0, v[26:27]
	global_store_dwordx2 v[18:19], v[16:17], off
	v_mul_f32_e32 v16, 0x3d372713, v8
	v_mul_f32_e32 v17, 0x3d372713, v9
	v_mul_f32_e32 v16, v8, v16
	v_mul_f32_e32 v17, v9, v17
	v_fma_f32 v16, v8, v16, v8
	v_fma_f32 v17, v9, v17, v9
	v_mul_f32_e32 v16, 0x3f4c422a, v16
	v_mul_f32_e32 v17, 0x3f4c422a, v17
	v_add_f32_e32 v16, v16, v16
	v_add_f32_e32 v17, v17, v17
	v_mul_f32_e32 v16, 0xbfb8aa3b, v16
	v_mul_f32_e32 v17, 0xbfb8aa3b, v17
	v_exp_f32_e32 v16, v16
	v_exp_f32_e32 v17, v17
	v_add_f32_e32 v16, 1.0, v16
	v_add_f32_e32 v17, 1.0, v17
	v_rcp_f32_e32 v16, v16
	v_rcp_f32_e32 v17, v17
	s_nop 0
	v_pk_mul_f32 v[8:9], v[8:9], v[16:17]
	s_nop 0
	v_cvt_pk_bf16_f32 v8, v8, v9
	v_mul_f32_e32 v9, 0x3d372713, v10
	v_mul_f32_e32 v9, v10, v9
	v_fma_f32 v9, v10, v9, v10
	v_mul_f32_e32 v9, 0x3f4c422a, v9
	v_add_f32_e32 v9, v9, v9
	v_mul_f32_e32 v9, 0xbfb8aa3b, v9
	v_exp_f32_e32 v9, v9
	s_nop 0
	v_add_f32_e32 v9, 1.0, v9
	v_rcp_f32_e32 v16, v9
	v_mul_f32_e32 v9, 0x3d372713, v11
	v_mul_f32_e32 v9, v11, v9
	v_fma_f32 v9, v11, v9, v11
	v_mul_f32_e32 v9, 0x3f4c422a, v9
	v_add_f32_e32 v9, v9, v9
	v_mul_f32_e32 v9, 0xbfb8aa3b, v9
	v_exp_f32_e32 v9, v9
	s_nop 0
	v_add_f32_e32 v9, 1.0, v9
	v_rcp_f32_e32 v17, v9
	s_nop 0
	v_pk_mul_f32 v[10:11], v[10:11], v[16:17]
	s_nop 0
	v_cvt_pk_bf16_f32 v9, v10, v11
	v_lshl_add_u64 v[10:11], v[84:85], 0, v[26:27]
	global_store_dwordx2 v[10:11], v[8:9], off
	v_mul_f32_e32 v8, 0x3d372713, v36
	v_mul_f32_e32 v9, 0x3d372713, v37
	v_mul_f32_e32 v8, v36, v8
	v_mul_f32_e32 v9, v37, v9
	v_fma_f32 v8, v36, v8, v36
	v_fma_f32 v9, v37, v9, v37
	v_mul_f32_e32 v8, 0x3f4c422a, v8
	v_mul_f32_e32 v9, 0x3f4c422a, v9
	v_add_f32_e32 v8, v8, v8
	v_add_f32_e32 v9, v9, v9
	v_mul_f32_e32 v8, 0xbfb8aa3b, v8
	v_mul_f32_e32 v9, 0xbfb8aa3b, v9
	v_exp_f32_e32 v8, v8
	v_exp_f32_e32 v9, v9
	v_add_f32_e32 v8, 1.0, v8
	v_add_f32_e32 v9, 1.0, v9
	v_rcp_f32_e32 v8, v8
	v_rcp_f32_e32 v9, v9
	s_nop 0
	v_pk_mul_f32 v[8:9], v[36:37], v[8:9]
	s_nop 0
	v_cvt_pk_bf16_f32 v8, v8, v9
	v_mul_f32_e32 v9, 0x3d372713, v38
	v_mul_f32_e32 v9, v38, v9
	v_fma_f32 v9, v38, v9, v38
	v_mul_f32_e32 v9, 0x3f4c422a, v9
	v_add_f32_e32 v9, v9, v9
	v_mul_f32_e32 v9, 0xbfb8aa3b, v9
	v_exp_f32_e32 v9, v9
	s_nop 0
	v_add_f32_e32 v9, 1.0, v9
	v_rcp_f32_e32 v10, v9
	v_mul_f32_e32 v9, 0x3d372713, v39
	v_mul_f32_e32 v9, v39, v9
	v_fma_f32 v9, v39, v9, v39
	v_mul_f32_e32 v9, 0x3f4c422a, v9
	v_add_f32_e32 v9, v9, v9
	v_mul_f32_e32 v9, 0xbfb8aa3b, v9
	v_exp_f32_e32 v9, v9
	s_nop 0
	v_add_f32_e32 v9, 1.0, v9
	v_rcp_f32_e32 v11, v9
	s_nop 0
	v_pk_mul_f32 v[10:11], v[38:39], v[10:11]
	s_nop 0
	v_cvt_pk_bf16_f32 v9, v10, v11
	v_or_b32_e32 v10, 0x1800, v92
	v_mov_b32_e32 v11, v93
	v_lshl_add_u64 v[16:17], v[94:95], 0, v[10:11]
	global_store_dwordx2 v[16:17], v[8:9], off
	v_mul_f32_e32 v8, 0x3d372713, v28
	v_mul_f32_e32 v9, 0x3d372713, v29
	v_mul_f32_e32 v8, v28, v8
	v_mul_f32_e32 v9, v29, v9
	v_fma_f32 v8, v28, v8, v28
	v_fma_f32 v9, v29, v9, v29
	v_mul_f32_e32 v8, 0x3f4c422a, v8
	v_mul_f32_e32 v9, 0x3f4c422a, v9
	v_add_f32_e32 v8, v8, v8
	v_add_f32_e32 v9, v9, v9
	v_mul_f32_e32 v8, 0xbfb8aa3b, v8
	v_mul_f32_e32 v9, 0xbfb8aa3b, v9
	v_exp_f32_e32 v8, v8
	v_exp_f32_e32 v9, v9
	v_or_b32_e32 v92, 0x1c00, v92
	v_add_f32_e32 v8, 1.0, v8
	v_add_f32_e32 v9, 1.0, v9
	v_rcp_f32_e32 v8, v8
	v_rcp_f32_e32 v9, v9
	s_nop 0
	v_pk_mul_f32 v[8:9], v[28:29], v[8:9]
	s_nop 0
	v_cvt_pk_bf16_f32 v8, v8, v9
	v_mul_f32_e32 v9, 0x3d372713, v30
	v_mul_f32_e32 v9, v30, v9
	v_fma_f32 v9, v30, v9, v30
	v_mul_f32_e32 v9, 0x3f4c422a, v9
	v_add_f32_e32 v9, v9, v9
	v_mul_f32_e32 v9, 0xbfb8aa3b, v9
	v_exp_f32_e32 v9, v9
	s_nop 0
	v_add_f32_e32 v9, 1.0, v9
	v_rcp_f32_e32 v16, v9
	v_mul_f32_e32 v9, 0x3d372713, v31
	v_mul_f32_e32 v9, v31, v9
	v_fma_f32 v9, v31, v9, v31
	v_mul_f32_e32 v9, 0x3f4c422a, v9
	v_add_f32_e32 v9, v9, v9
	v_mul_f32_e32 v9, 0xbfb8aa3b, v9
	v_exp_f32_e32 v9, v9
	s_nop 0
	v_add_f32_e32 v9, 1.0, v9
	v_rcp_f32_e32 v17, v9
; __device__ __forceinline__ unsigned pk2(float lo, float hi) { const f32x2 v = {lo, hi}; return __builtin_bit_cast(unsigned, __builtin_convertvector(v, bf16x2_t)); }
; __device__ __forceinline__ float gelu_tanh(float x) { const float y = 0.7978845608028654f * (x + 0.044715f * x * x * x); return x * sigmoidf_(2.f * y); }
;     __device__ __forceinline__ unsigned char* ws() const { return (unsigned char*)(__attribute__((address_space(1))) unsigned char*)get(35); }
; __device__ __forceinline__ void s5_out_unit(const PA& a, int unit, LAS unsigned char* lds, int tid_) {
;     ...
;     bf16* YG = (bf16*)(a.ws() + WS_YG);
; #pragma unroll
;     for (int i = 0; i < 8; ++i)
; #pragma unroll
;         for (int nt = 0; nt < 3; ++nt) { const int chunk = nb * 48 + nt * 16 + fr; const size_t row = (size_t)chunk * 64 + 8 * w + i; const f32x4 v = acc[i][nt];
;             *(u32x2*)(YG + row * 512 + g * 16 + kg * 4) = (u32x2){pk2(gelu_tanh(v.x), gelu_tanh(v.y)), pk2(gelu_tanh(v.z), gelu_tanh(v.w))}; }
	s_nop 0
	v_pk_mul_f32 v[16:17], v[30:31], v[16:17]
	s_nop 0
	v_cvt_pk_bf16_f32 v9, v16, v17
	v_lshl_add_u64 v[16:17], v[88:89], 0, v[10:11]
	global_store_dwordx2 v[16:17], v[8:9], off
	v_mul_f32_e32 v8, 0x3d372713, v20
	v_mul_f32_e32 v9, 0x3d372713, v21
	v_mul_f32_e32 v8, v20, v8
	v_mul_f32_e32 v9, v21, v9
	v_fma_f32 v8, v20, v8, v20
	v_fma_f32 v9, v21, v9, v21
	v_mul_f32_e32 v8, 0x3f4c422a, v8
	v_mul_f32_e32 v9, 0x3f4c422a, v9
	v_add_f32_e32 v8, v8, v8
	v_add_f32_e32 v9, v9, v9
	v_mul_f32_e32 v8, 0xbfb8aa3b, v8
	v_mul_f32_e32 v9, 0xbfb8aa3b, v9
	v_exp_f32_e32 v8, v8
	v_exp_f32_e32 v9, v9
	v_lshl_add_u64 v[10:11], v[84:85], 0, v[10:11]
	v_add_f32_e32 v8, 1.0, v8
	v_add_f32_e32 v9, 1.0, v9
	v_rcp_f32_e32 v8, v8
	v_rcp_f32_e32 v9, v9
	s_nop 0
	v_pk_mul_f32 v[8:9], v[20:21], v[8:9]
	s_nop 0
	v_cvt_pk_bf16_f32 v8, v8, v9
	v_mul_f32_e32 v9, 0x3d372713, v22
	v_mul_f32_e32 v9, v22, v9
	v_fma_f32 v9, v22, v9, v22
	v_mul_f32_e32 v9, 0x3f4c422a, v9
	v_add_f32_e32 v9, v9, v9
	v_mul_f32_e32 v9, 0xbfb8aa3b, v9
	v_exp_f32_e32 v9, v9
	s_nop 0
	v_add_f32_e32 v9, 1.0, v9
	v_rcp_f32_e32 v16, v9
	v_mul_f32_e32 v9, 0x3d372713, v23
	v_mul_f32_e32 v9, v23, v9
	v_fma_f32 v9, v23, v9, v23
	v_mul_f32_e32 v9, 0x3f4c422a, v9
	v_add_f32_e32 v9, v9, v9
	v_mul_f32_e32 v9, 0xbfb8aa3b, v9
	v_exp_f32_e32 v9, v9
	s_nop 0
	v_add_f32_e32 v9, 1.0, v9
	v_rcp_f32_e32 v17, v9
	s_nop 0
	v_pk_mul_f32 v[16:17], v[22:23], v[16:17]
	s_nop 0
	v_cvt_pk_bf16_f32 v9, v16, v17
	global_store_dwordx2 v[10:11], v[8:9], off
	v_mul_f32_e32 v8, 0x3d372713, v12
	v_mul_f32_e32 v9, 0x3d372713, v13
	v_mul_f32_e32 v8, v12, v8
	v_mul_f32_e32 v9, v13, v9
	v_fma_f32 v8, v12, v8, v12
	v_fma_f32 v9, v13, v9, v13
	v_mul_f32_e32 v8, 0x3f4c422a, v8
	v_mul_f32_e32 v9, 0x3f4c422a, v9
	v_add_f32_e32 v8, v8, v8
	v_add_f32_e32 v9, v9, v9
	v_mul_f32_e32 v8, 0xbfb8aa3b, v8
	v_mul_f32_e32 v9, 0xbfb8aa3b, v9
	v_exp_f32_e32 v8, v8
	v_exp_f32_e32 v9, v9
	v_add_f32_e32 v8, 1.0, v8
	v_add_f32_e32 v9, 1.0, v9
	v_rcp_f32_e32 v8, v8
	v_rcp_f32_e32 v9, v9
	s_nop 0
	v_pk_mul_f32 v[8:9], v[12:13], v[8:9]
	s_nop 0
	v_cvt_pk_bf16_f32 v8, v8, v9
	v_mul_f32_e32 v9, 0x3d372713, v14
	v_mul_f32_e32 v9, v14, v9
	v_fma_f32 v9, v14, v9, v14
	v_mul_f32_e32 v9, 0x3f4c422a, v9
	v_add_f32_e32 v9, v9, v9
	v_mul_f32_e32 v9, 0xbfb8aa3b, v9
	v_exp_f32_e32 v9, v9
	s_nop 0
	v_add_f32_e32 v9, 1.0, v9
	v_rcp_f32_e32 v10, v9
	v_mul_f32_e32 v9, 0x3d372713, v15
	v_mul_f32_e32 v9, v15, v9
	v_fma_f32 v9, v15, v9, v15
	v_mul_f32_e32 v9, 0x3f4c422a, v9
	v_add_f32_e32 v9, v9, v9
	v_mul_f32_e32 v9, 0xbfb8aa3b, v9
	v_exp_f32_e32 v9, v9
	s_nop 0
	v_add_f32_e32 v9, 1.0, v9
	v_rcp_f32_e32 v11, v9
	s_nop 0
	v_pk_mul_f32 v[10:11], v[14:15], v[10:11]
	s_nop 0
	v_cvt_pk_bf16_f32 v9, v10, v11
	v_lshl_add_u64 v[10:11], v[94:95], 0, v[92:93]
	global_store_dwordx2 v[10:11], v[8:9], off
	v_mul_f32_e32 v8, 0x3d372713, v4
	v_mul_f32_e32 v9, 0x3d372713, v5
	v_mul_f32_e32 v8, v4, v8
	v_mul_f32_e32 v9, v5, v9
	v_fma_f32 v8, v4, v8, v4
	v_fma_f32 v9, v5, v9, v5
	v_mul_f32_e32 v8, 0x3f4c422a, v8
	v_mul_f32_e32 v9, 0x3f4c422a, v9
	v_add_f32_e32 v8, v8, v8
	v_add_f32_e32 v9, v9, v9
	v_mul_f32_e32 v8, 0xbfb8aa3b, v8
	v_mul_f32_e32 v9, 0xbfb8aa3b, v9
	v_exp_f32_e32 v8, v8
	v_exp_f32_e32 v9, v9
	v_add_f32_e32 v8, 1.0, v8
	v_add_f32_e32 v9, 1.0, v9
	v_rcp_f32_e32 v8, v8
	v_rcp_f32_e32 v9, v9
	s_nop 0
	v_pk_mul_f32 v[4:5], v[4:5], v[8:9]
	s_nop 0
	v_cvt_pk_bf16_f32 v4, v4, v5
	v_mul_f32_e32 v5, 0x3d372713, v6
	v_mul_f32_e32 v5, v6, v5
	v_fma_f32 v5, v6, v5, v6
	v_mul_f32_e32 v5, 0x3f4c422a, v5
	v_add_f32_e32 v5, v5, v5
	v_mul_f32_e32 v5, 0xbfb8aa3b, v5
	v_exp_f32_e32 v5, v5
	s_nop 0
	v_add_f32_e32 v5, 1.0, v5
	v_rcp_f32_e32 v8, v5
	v_mul_f32_e32 v5, 0x3d372713, v7
	v_mul_f32_e32 v5, v7, v5
	v_fma_f32 v5, v7, v5, v7
	v_mul_f32_e32 v5, 0x3f4c422a, v5
	v_add_f32_e32 v5, v5, v5
	v_mul_f32_e32 v5, 0xbfb8aa3b, v5
	v_exp_f32_e32 v5, v5
	s_nop 0
	v_add_f32_e32 v5, 1.0, v5
	v_rcp_f32_e32 v9, v5
	s_nop 0
	v_pk_mul_f32 v[6:7], v[6:7], v[8:9]
	s_nop 0
	v_cvt_pk_bf16_f32 v5, v6, v7
	v_lshl_add_u64 v[6:7], v[88:89], 0, v[92:93]
	global_store_dwordx2 v[6:7], v[4:5], off
	v_mul_f32_e32 v4, 0x3d372713, v0
	v_mul_f32_e32 v5, 0x3d372713, v1
	v_mul_f32_e32 v4, v0, v4
	v_mul_f32_e32 v5, v1, v5
	v_fma_f32 v4, v0, v4, v0
	v_fma_f32 v5, v1, v5, v1
	v_mul_f32_e32 v4, 0x3f4c422a, v4
	v_mul_f32_e32 v5, 0x3f4c422a, v5
	v_add_f32_e32 v4, v4, v4
	v_add_f32_e32 v5, v5, v5
	v_mul_f32_e32 v4, 0xbfb8aa3b, v4
	v_mul_f32_e32 v5, 0xbfb8aa3b, v5
	v_exp_f32_e32 v4, v4
	v_exp_f32_e32 v5, v5
	v_add_f32_e32 v4, 1.0, v4
	v_add_f32_e32 v5, 1.0, v5
	v_rcp_f32_e32 v4, v4
	v_rcp_f32_e32 v5, v5
	s_nop 0
	v_pk_mul_f32 v[0:1], v[0:1], v[4:5]
	s_nop 0
	v_cvt_pk_bf16_f32 v0, v0, v1
	v_mul_f32_e32 v1, 0x3d372713, v2
	v_mul_f32_e32 v1, v2, v1
	v_fma_f32 v1, v2, v1, v2
	v_mul_f32_e32 v1, 0x3f4c422a, v1
	v_add_f32_e32 v1, v1, v1
	v_mul_f32_e32 v1, 0xbfb8aa3b, v1
	v_exp_f32_e32 v1, v1
	s_nop 0
	v_add_f32_e32 v1, 1.0, v1
	v_rcp_f32_e32 v4, v1
	v_mul_f32_e32 v1, 0x3d372713, v3
	v_mul_f32_e32 v1, v3, v1
	v_fma_f32 v1, v3, v1, v3
	v_mul_f32_e32 v1, 0x3f4c422a, v1
	v_add_f32_e32 v1, v1, v1
	v_mul_f32_e32 v1, 0xbfb8aa3b, v1
	v_exp_f32_e32 v1, v1
	s_nop 0
	v_add_f32_e32 v1, 1.0, v1
	v_rcp_f32_e32 v5, v1
	s_nop 0
	v_pk_mul_f32 v[2:3], v[2:3], v[4:5]
	s_nop 0
	v_cvt_pk_bf16_f32 v1, v2, v3
	v_lshl_add_u64 v[2:3], v[84:85], 0, v[92:93]
	global_store_dwordx2 v[2:3], v[0:1], off

; __device__ __forceinline__ unsigned pk2(float lo, float hi) { const f32x2 v = {lo, hi}; return __builtin_bit_cast(unsigned, __builtin_convertvector(v, bf16x2_t)); }
;     __device__ __forceinline__ unsigned char* ws() const { return (unsigned char*)(__attribute__((address_space(1))) unsigned char*)get(35); }
; __device__ __forceinline__ void merge_ctx_rows(const PA& a, int gw, int NGW, int lane) {
;     const float* part = (const float*)(a.ws() + WS_PART); bf16* MGp = (bf16*)(a.ws() + WS_MG);
;     for (int rc = gw; rc < NCTX; rc += NGW) {
;         u32x2* o8 = (u32x2*)(MGp + (size_t)(NLAT + rc) * D) + lane; f32x4 v[8];
; #pragma unroll
;         for (int j = 0; j < 8; ++j) { const int col = (lane + 64 * j) * 4; const float* pp = part + (size_t)rc * D + col;
;             v[j] = ((*(const f32x4*)pp + *(const f32x4*)(pp + (size_t)NCTX * D)) + *(const f32x4*)(pp + (size_t)2 * NCTX * D)) + *(const f32x4*)(pp + (size_t)3 * NCTX * D); }
; #pragma unroll
;         for (int j = 0; j < 8; ++j) o8[64 * j] = (u32x2){pk2(v[j].x, v[j].y), pk2(v[j].z, v[j].w)};
;     }
.LBB0_1234:
	global_load_dwordx4 v[48:51], v[2:3], off
	v_add_co_u32_e32 v20, vcc, 0x800000, v2
	s_nop 0
	v_addc_co_u32_e32 v21, vcc, 0, v3, vcc
	global_load_dwordx4 v[52:55], v[20:21], off
	v_add_co_u32_e32 v24, vcc, 0x1000000, v2
	s_mov_b32 s1, 0x801000
	s_nop 0
	v_addc_co_u32_e32 v25, vcc, 0, v3, vcc
	global_load_dwordx4 v[56:59], v[24:25], off
	v_add_co_u32_e32 v26, vcc, 0x1800000, v2
	s_add_i32 s12, s0, 0x8000
	s_nop 0
	v_addc_co_u32_e32 v27, vcc, 0, v3, vcc
	global_load_dwordx4 v[60:63], v[26:27], off
	global_load_dwordx4 v[64:67], v[2:3], off offset:1024
	global_load_dwordx4 v[68:71], v[20:21], off offset:1024
	global_load_dwordx4 v[72:75], v[24:25], off offset:1024
	global_load_dwordx4 v[76:79], v[26:27], off offset:1024
	global_load_dwordx4 v[80:83], v[2:3], off offset:2048
	global_load_dwordx4 v[84:87], v[20:21], off offset:2048
	global_load_dwordx4 v[88:91], v[24:25], off offset:2048
	global_load_dwordx4 v[92:95], v[26:27], off offset:2048
	global_load_dwordx4 v[96:99], v[2:3], off offset:3072
	global_load_dwordx4 v[100:103], v[20:21], off offset:3072
	global_load_dwordx4 v[104:107], v[24:25], off offset:3072
	global_load_dwordx4 v[108:111], v[26:27], off offset:3072
	v_add_co_u32_e32 v28, vcc, s66, v2
	s_ashr_i32 s13, s12, 31
	s_nop 0
	v_addc_co_u32_e32 v29, vcc, 0, v3, vcc
	global_load_dwordx4 v[112:115], v[28:29], off
	v_add_co_u32_e32 v30, vcc, s1, v2
	s_mov_b32 s1, 0x1001000
	s_nop 0
	v_addc_co_u32_e32 v31, vcc, 0, v3, vcc
	global_load_dwordx4 v[116:119], v[30:31], off
	v_add_co_u32_e32 v32, vcc, s1, v2
	s_mov_b32 s1, 0x1801000
	s_nop 0
	v_addc_co_u32_e32 v33, vcc, 0, v3, vcc
	global_load_dwordx4 v[120:123], v[32:33], off
	v_add_co_u32_e32 v34, vcc, s1, v2
	s_lshl_b64 s[12:13], s[12:13], 12
	s_nop 0
	v_addc_co_u32_e32 v35, vcc, 0, v3, vcc
	global_load_dwordx4 v[124:127], v[34:35], off
	global_load_dwordx4 v[128:131], v[28:29], off offset:1024
	global_load_dwordx4 v[132:135], v[30:31], off offset:1024
	global_load_dwordx4 v[136:139], v[32:33], off offset:1024
	global_load_dwordx4 v[140:143], v[34:35], off offset:1024
	global_load_dwordx4 v[144:147], v[28:29], off offset:2048
	global_load_dwordx4 v[148:151], v[30:31], off offset:2048
	global_load_dwordx4 v[152:155], v[32:33], off offset:2048
	global_load_dwordx4 v[156:159], v[34:35], off offset:2048
	global_load_dwordx4 v[160:163], v[28:29], off offset:3072
	global_load_dwordx4 v[164:167], v[30:31], off offset:3072
	global_load_dwordx4 v[168:171], v[32:33], off offset:3072
	global_load_dwordx4 v[172:175], v[34:35], off offset:3072
	s_add_i32 s0, s0, s8
	s_cmpk_lt_i32 s0, 0x400
	s_waitcnt vmcnt(30)
	v_pk_add_f32 v[10:11], v[50:51], v[54:55]
	v_pk_add_f32 v[8:9], v[48:49], v[52:53]
	s_waitcnt vmcnt(29)
	v_pk_add_f32 v[10:11], v[10:11], v[58:59]
	v_pk_add_f32 v[12:13], v[8:9], v[56:57]
	s_waitcnt vmcnt(28)
	v_pk_add_f32 v[4:5], v[10:11], v[62:63]
	v_pk_add_f32 v[6:7], v[12:13], v[60:61]
	v_cvt_pk_bf16_f32 v6, v6, v7
	v_cvt_pk_bf16_f32 v7, v4, v5
	s_waitcnt vmcnt(26)
	v_pk_add_f32 v[14:15], v[66:67], v[70:71]
	v_pk_add_f32 v[12:13], v[64:65], v[68:69]
	s_waitcnt vmcnt(25)
	v_pk_add_f32 v[14:15], v[14:15], v[74:75]
	v_pk_add_f32 v[16:17], v[12:13], v[72:73]
	s_waitcnt vmcnt(24)
	v_pk_add_f32 v[8:9], v[14:15], v[78:79]
	v_pk_add_f32 v[10:11], v[16:17], v[76:77]
	v_cvt_pk_bf16_f32 v4, v10, v11
	v_cvt_pk_bf16_f32 v5, v8, v9
	s_waitcnt vmcnt(22)
	v_pk_add_f32 v[18:19], v[82:83], v[86:87]
	v_pk_add_f32 v[16:17], v[80:81], v[84:85]
	s_waitcnt vmcnt(21)
	v_pk_add_f32 v[18:19], v[18:19], v[90:91]
	v_pk_add_f32 v[22:23], v[16:17], v[88:89]
	s_waitcnt vmcnt(20)
	v_pk_add_f32 v[12:13], v[18:19], v[94:95]
	v_pk_add_f32 v[14:15], v[22:23], v[92:93]
	s_nop 0
	v_lshl_add_u64 v[2:3], v[2:3], 0, s[10:11]
	s_waitcnt vmcnt(18)
	v_pk_add_f32 v[22:23], v[98:99], v[102:103]
	v_pk_add_f32 v[20:21], v[96:97], v[100:101]
	s_waitcnt vmcnt(17)
	v_pk_add_f32 v[22:23], v[22:23], v[106:107]
	v_pk_add_f32 v[24:25], v[20:21], v[104:105]
	s_waitcnt vmcnt(16)
	v_pk_add_f32 v[16:17], v[22:23], v[110:111]
	v_pk_add_f32 v[18:19], v[24:25], v[108:109]
	s_waitcnt vmcnt(14)
	v_pk_add_f32 v[26:27], v[114:115], v[118:119]
	v_pk_add_f32 v[24:25], v[112:113], v[116:117]
	s_waitcnt vmcnt(13)
	v_pk_add_f32 v[26:27], v[26:27], v[122:123]
	v_pk_add_f32 v[24:25], v[24:25], v[120:121]
	s_waitcnt vmcnt(12)
	v_pk_add_f32 v[36:37], v[26:27], v[126:127]
	v_pk_add_f32 v[38:39], v[24:25], v[124:125]
	s_waitcnt vmcnt(10)
	v_pk_add_f32 v[26:27], v[130:131], v[134:135]
	v_pk_add_f32 v[24:25], v[128:129], v[132:133]
	s_waitcnt vmcnt(9)
	v_pk_add_f32 v[26:27], v[26:27], v[138:139]
	v_pk_add_f32 v[24:25], v[24:25], v[136:137]
	s_waitcnt vmcnt(8)
	v_pk_add_f32 v[40:41], v[26:27], v[142:143]
	v_pk_add_f32 v[42:43], v[24:25], v[140:141]
	s_waitcnt vmcnt(6)
	v_pk_add_f32 v[26:27], v[146:147], v[150:151]
	v_pk_add_f32 v[24:25], v[144:145], v[148:149]
	s_waitcnt vmcnt(5)
	v_pk_add_f32 v[26:27], v[26:27], v[154:155]
	v_pk_add_f32 v[24:25], v[24:25], v[152:153]
	s_waitcnt vmcnt(4)
	v_pk_add_f32 v[44:45], v[26:27], v[158:159]
	v_pk_add_f32 v[46:47], v[24:25], v[156:157]
	s_waitcnt vmcnt(2)
	v_pk_add_f32 v[26:27], v[162:163], v[166:167]
	v_pk_add_f32 v[24:25], v[160:161], v[164:165]
	s_waitcnt vmcnt(1)
	v_pk_add_f32 v[26:27], v[26:27], v[170:171]
	v_pk_add_f32 v[24:25], v[24:25], v[168:169]
	s_waitcnt vmcnt(0)
	v_pk_add_f32 v[20:21], v[24:25], v[172:173]
	v_lshl_add_u64 v[24:25], v[0:1], 0, s[12:13]
	global_store_dwordx2 v[24:25], v[4:5], off offset:512
	v_cvt_pk_bf16_f32 v4, v14, v15
	v_cvt_pk_bf16_f32 v5, v12, v13
	global_store_dwordx2 v[24:25], v[4:5], off offset:1024
	v_cvt_pk_bf16_f32 v4, v18, v19
	v_cvt_pk_bf16_f32 v5, v16, v17
	global_store_dwordx2 v[24:25], v[4:5], off offset:1536
	v_cvt_pk_bf16_f32 v4, v38, v39
	v_cvt_pk_bf16_f32 v5, v36, v37
	global_store_dwordx2 v[24:25], v[4:5], off offset:2048
	v_cvt_pk_bf16_f32 v4, v42, v43
	v_cvt_pk_bf16_f32 v5, v40, v41
	v_pk_add_f32 v[22:23], v[26:27], v[174:175]
	global_store_dwordx2 v[24:25], v[4:5], off offset:2560
	v_cvt_pk_bf16_f32 v4, v46, v47
	v_cvt_pk_bf16_f32 v5, v44, v45
	global_store_dwordx2 v[24:25], v[4:5], off offset:3072
	v_cvt_pk_bf16_f32 v4, v20, v21
	v_cvt_pk_bf16_f32 v5, v22, v23
	global_store_dwordx2 v[24:25], v[6:7], off
	global_store_dwordx2 v[24:25], v[4:5], off offset:3584
	s_cbranch_scc1 .LBB0_1234

; __device__ __forceinline__ unsigned pk2(float lo, float hi) { const f32x2 v = {lo, hi}; return __builtin_bit_cast(unsigned, __builtin_convertvector(v, bf16x2_t)); }
; __device__ __forceinline__ float wave_sum(float v) { v += shx<1>(v); v += shx<2>(v); v += shx<4>(v); v += shx<8>(v); v += shx<16>(v); v += shx<32>(v); return v; }
;     __device__ __forceinline__ unsigned char* ws() const { return (unsigned char*)(__attribute__((address_space(1))) unsigned char*)get(35); }
; __device__ __forceinline__ void outproj_ctx_rows(const PA& a, int layer, int gw, int NGW, int lane) {
;     ...
;     for (int rc = gw; rc < NCTX; rc += NGW) {
;         const f32x4* xs = (const f32x4*)(srcb + (size_t)rc * D) + lane; f32x4* xr = (f32x4*)(a.ws() + WS_XC + (size_t)rc * D * 4) + lane; f32x4 v[8]; float ss = 0.f;
; #pragma unroll
;         for (int j = 0; j < 8; ++j) { const int col = (lane + 64 * j) * 4; const float* pp = part + (size_t)rc * D + col;
;             const f32x4 p = ((*(const f32x4*)pp + *(const f32x4*)(pp + (size_t)NCTX * D)) + *(const f32x4*)(pp + (size_t)2 * NCTX * D)) + *(const f32x4*)(pp + (size_t)3 * NCTX * D);
;             v[j] = xs[64 * j] + *(const f32x4*)(mv + 2 * D + col) * p; }
; #pragma unroll
;         for (int j = 0; j < 8; ++j) { xr[64 * j] = v[j]; ss += (v[j].x * v[j].x + v[j].y * v[j].y) + (v[j].z * v[j].z + v[j].w * v[j].w); }
;         const float sm = wave_sum(ss); if (lane == 0) ((float*)(a.ws() + WS_RS2))[NLAT + rc] = 1.f / sqrtf(sm * (1.f / D) + EPS);
;         u32x2* o8 = (u32x2*)(H + (size_t)(NLAT + rc) * D) + lane;
; #pragma unroll
;         for (int j = 0; j < 8; ++j) { const int col = (lane + 64 * j) * 4;
;             const f32x4 y = v[j] * *(const f32x4*)(ng + col) * (*(const f32x4*)(mv + 4 * D + col) + 1.f);
;             o8[64 * j] = (u32x2){pk2(y.x, y.y), pk2(y.z, y.w)}; }
.LBB0_1414:
	s_or_b64 exec, exec, s[22:23]
	global_load_dwordx4 v[92:95], v[54:55], off
	global_load_dwordx4 v[96:99], v[56:57], off
	global_load_dwordx4 v[100:103], v[54:55], off offset:1024
	global_load_dwordx4 v[104:107], v[58:59], off
	global_load_dwordx4 v[108:111], v[54:55], off offset:2048
	global_load_dwordx4 v[112:115], v[60:61], off
	global_load_dwordx4 v[116:119], v[54:55], off offset:3072
	global_load_dwordx4 v[120:123], v[62:63], off
	global_load_dwordx4 v[124:127], v[64:65], off
	global_load_dwordx4 v[128:131], v[66:67], off
	global_load_dwordx4 v[132:135], v[68:69], off
	global_load_dwordx4 v[136:139], v[70:71], off
	global_load_dwordx4 v[140:143], v[72:73], off
	global_load_dwordx4 v[144:147], v[74:75], off
	global_load_dwordx4 v[148:151], v[76:77], off
	global_load_dwordx4 v[152:155], v[78:79], off
	s_add_i32 s6, s14, 0x8000
	s_ashr_i32 s7, s6, 31
	s_lshl_b64 s[6:7], s[6:7], 12
	s_waitcnt lgkmcnt(0)
	v_lshl_add_u64 v[32:33], v[36:37], 0, s[6:7]
	s_add_i32 s14, s14, s16
	s_add_u32 s24, s24, s18
	s_addc_u32 s25, s25, s19
	v_lshl_add_u64 v[80:81], v[80:81], 0, s[20:21]
	s_cmpk_lt_i32 s14, 0x400
	s_waitcnt vmcnt(15)
	v_pk_mul_f32 v[34:35], v[2:3], v[94:95]
	v_pk_mul_f32 v[82:83], v[0:1], v[92:93]
	s_waitcnt vmcnt(14)
	v_pk_add_f32 v[2:3], v[98:99], 1.0 op_sel_hi:[1,0]
	v_pk_add_f32 v[0:1], v[96:97], 1.0 op_sel_hi:[1,0]
	v_pk_mul_f32 v[2:3], v[34:35], v[2:3]
	v_pk_mul_f32 v[0:1], v[82:83], v[0:1]
	s_nop 0
	v_cvt_pk_bf16_f32 v0, v0, v1
	v_cvt_pk_bf16_f32 v1, v2, v3
	global_store_dwordx2 v[32:33], v[0:1], off
	s_waitcnt vmcnt(14)
	v_pk_mul_f32 v[10:11], v[10:11], v[102:103]
	v_pk_mul_f32 v[8:9], v[8:9], v[100:101]
	s_waitcnt vmcnt(13)
	v_pk_add_f32 v[2:3], v[106:107], 1.0 op_sel_hi:[1,0]
	v_pk_add_f32 v[0:1], v[104:105], 1.0 op_sel_hi:[1,0]
	v_pk_mul_f32 v[2:3], v[10:11], v[2:3]
	v_pk_mul_f32 v[0:1], v[8:9], v[0:1]
	s_nop 0
	v_cvt_pk_bf16_f32 v0, v0, v1
	v_cvt_pk_bf16_f32 v1, v2, v3
	global_store_dwordx2 v[32:33], v[0:1], off offset:512
	s_waitcnt vmcnt(13)
	v_pk_mul_f32 v[6:7], v[6:7], v[110:111]
	v_pk_mul_f32 v[4:5], v[4:5], v[108:109]
	s_waitcnt vmcnt(12)
	v_pk_add_f32 v[2:3], v[114:115], 1.0 op_sel_hi:[1,0]
	v_pk_add_f32 v[0:1], v[112:113], 1.0 op_sel_hi:[1,0]
	v_pk_mul_f32 v[2:3], v[6:7], v[2:3]
	v_pk_mul_f32 v[0:1], v[4:5], v[0:1]
	s_nop 0
	v_cvt_pk_bf16_f32 v0, v0, v1
	v_cvt_pk_bf16_f32 v1, v2, v3
	global_store_dwordx2 v[32:33], v[0:1], off offset:1024
	s_waitcnt vmcnt(12)
	v_pk_mul_f32 v[4:5], v[14:15], v[118:119]
	v_pk_mul_f32 v[6:7], v[12:13], v[116:117]
	s_waitcnt vmcnt(11)
	v_pk_add_f32 v[2:3], v[122:123], 1.0 op_sel_hi:[1,0]
	v_pk_add_f32 v[0:1], v[120:121], 1.0 op_sel_hi:[1,0]
	v_pk_mul_f32 v[2:3], v[4:5], v[2:3]
	v_pk_mul_f32 v[0:1], v[6:7], v[0:1]
	s_nop 0
	v_cvt_pk_bf16_f32 v0, v0, v1
	v_cvt_pk_bf16_f32 v1, v2, v3
	global_store_dwordx2 v[32:33], v[0:1], off offset:1536
	s_waitcnt vmcnt(11)
	v_pk_mul_f32 v[4:5], v[18:19], v[126:127]
	v_pk_mul_f32 v[6:7], v[16:17], v[124:125]
	s_waitcnt vmcnt(10)
	v_pk_add_f32 v[2:3], v[130:131], 1.0 op_sel_hi:[1,0]
	v_pk_add_f32 v[0:1], v[128:129], 1.0 op_sel_hi:[1,0]
	v_pk_mul_f32 v[2:3], v[4:5], v[2:3]
	v_pk_mul_f32 v[0:1], v[6:7], v[0:1]
	s_nop 0
	v_cvt_pk_bf16_f32 v0, v0, v1
	v_cvt_pk_bf16_f32 v1, v2, v3
	global_store_dwordx2 v[32:33], v[0:1], off offset:2048
	s_waitcnt vmcnt(10)
	v_pk_mul_f32 v[4:5], v[22:23], v[134:135]
	v_pk_mul_f32 v[6:7], v[20:21], v[132:133]
	s_waitcnt vmcnt(9)
	v_pk_add_f32 v[2:3], v[138:139], 1.0 op_sel_hi:[1,0]
	v_pk_add_f32 v[0:1], v[136:137], 1.0 op_sel_hi:[1,0]
	v_pk_mul_f32 v[2:3], v[4:5], v[2:3]
	v_pk_mul_f32 v[0:1], v[6:7], v[0:1]
	s_nop 0
	v_cvt_pk_bf16_f32 v0, v0, v1
	v_cvt_pk_bf16_f32 v1, v2, v3
	global_store_dwordx2 v[32:33], v[0:1], off offset:2560
	s_waitcnt vmcnt(9)
	v_pk_mul_f32 v[4:5], v[26:27], v[142:143]
	v_pk_mul_f32 v[6:7], v[24:25], v[140:141]
	s_waitcnt vmcnt(8)
	v_pk_add_f32 v[2:3], v[146:147], 1.0 op_sel_hi:[1,0]
	v_pk_add_f32 v[0:1], v[144:145], 1.0 op_sel_hi:[1,0]
	v_pk_mul_f32 v[2:3], v[4:5], v[2:3]
	v_pk_mul_f32 v[0:1], v[6:7], v[0:1]
	s_nop 0
	v_cvt_pk_bf16_f32 v0, v0, v1
	v_cvt_pk_bf16_f32 v1, v2, v3
	global_store_dwordx2 v[32:33], v[0:1], off offset:3072
	s_waitcnt vmcnt(8)
	v_pk_mul_f32 v[4:5], v[30:31], v[150:151]
	v_pk_mul_f32 v[6:7], v[28:29], v[148:149]
	s_waitcnt vmcnt(7)
	v_pk_add_f32 v[2:3], v[154:155], 1.0 op_sel_hi:[1,0]
	v_pk_add_f32 v[0:1], v[152:153], 1.0 op_sel_hi:[1,0]
	v_pk_mul_f32 v[2:3], v[4:5], v[2:3]
	v_pk_mul_f32 v[0:1], v[6:7], v[0:1]
	s_nop 0
	v_cvt_pk_bf16_f32 v0, v0, v1
	v_cvt_pk_bf16_f32 v1, v2, v3
	global_store_dwordx2 v[32:33], v[0:1], off offset:3584
	s_cbranch_scc0 .LBB0_1417
;     __device__ __forceinline__ unsigned char* ws() const { return (unsigned char*)(__attribute__((address_space(1))) unsigned char*)get(35); }
; __device__ __forceinline__ void outproj_ctx_rows(const PA& a, int layer, int gw, int NGW, int lane) {
;     ...
;     for (int rc = gw; rc < NCTX; rc += NGW) {
;         const f32x4* xs = (const f32x4*)(srcb + (size_t)rc * D) + lane; f32x4* xr = (f32x4*)(a.ws() + WS_XC + (size_t)rc * D * 4) + lane; f32x4 v[8]; float ss = 0.f;
; #pragma unroll
;         for (int j = 0; j < 8; ++j) { const int col = (lane + 64 * j) * 4; const float* pp = part + (size_t)rc * D + col;
;             const f32x4 p = ((*(const f32x4*)pp + *(const f32x4*)(pp + (size_t)NCTX * D)) + *(const f32x4*)(pp + (size_t)2 * NCTX * D)) + *(const f32x4*)(pp + (size_t)3 * NCTX * D);
;             v[j] = xs[64 * j] + *(const f32x4*)(mv + 2 * D + col) * p; }
; #pragma unroll
;         for (int j = 0; j < 8; ++j) { xr[64 * j] = v[j]; ss += (v[j].x * v[j].x + v[j].y * v[j].y) + (v[j].z * v[j].z + v[j].w * v[j].w); }
.LBB0_1415:
	v_mov_b32 v0, 0
	v_lshl_add_u64 v[18:19], s[10:11], 0, v[80:81]
	v_add_u32_e32 v0, s79, v0
	ds_read_b32 v1, v0 offset:280
	ds_read_b32 v0, v0 offset:284
	v_add_co_u32_e32 v12, vcc, 0x56800000, v18
	v_lshl_add_u64 v[16:17], s[12:13], 0, v[80:81]
	s_nop 0
	v_addc_co_u32_e32 v13, vcc, 0, v19, vcc
	global_load_dwordx4 v[92:95], v[12:13], off
	v_add_co_u32_e32 v14, vcc, 0x57000000, v18
	s_waitcnt lgkmcnt(1)
	v_readfirstlane_b32 s6, v1
	v_addc_co_u32_e32 v15, vcc, 0, v19, vcc
	global_load_dwordx4 v[96:99], v[14:15], off
	s_waitcnt lgkmcnt(0)
	v_readfirstlane_b32 s7, v0
	v_add_co_u32_e32 v24, vcc, 0x57800000, v18
	s_waitcnt vmcnt(0)
	v_pk_add_f32 v[6:7], v[94:95], v[98:99]
	v_addc_co_u32_e32 v25, vcc, 0, v19, vcc
	global_load_dwordx4 v[100:103], v[24:25], off
	v_pk_add_f32 v[4:5], v[92:93], v[96:97]
	v_add_co_u32_e32 v26, vcc, 0x58000000, v18
	s_waitcnt vmcnt(0)
	v_pk_add_f32 v[6:7], v[6:7], v[102:103]
	v_addc_co_u32_e32 v27, vcc, 0, v19, vcc
	global_load_dwordx4 v[104:107], v[26:27], off
	global_load_dwordx4 v[108:111], v[16:17], off
	global_load_dwordx4 v[112:115], v[38:39], off
	global_load_dwordx4 v[116:119], v[12:13], off offset:1024
	global_load_dwordx4 v[120:123], v[14:15], off offset:1024
	global_load_dwordx4 v[124:127], v[24:25], off offset:1024
	global_load_dwordx4 v[128:131], v[26:27], off offset:1024
	global_load_dwordx4 v[132:135], v[16:17], off offset:1024
	global_load_dwordx4 v[136:139], v[40:41], off
	global_load_dwordx4 v[140:143], v[12:13], off offset:2048
	global_load_dwordx4 v[144:147], v[14:15], off offset:2048
	global_load_dwordx4 v[148:151], v[24:25], off offset:2048
	global_load_dwordx4 v[152:155], v[26:27], off offset:2048
	global_load_dwordx4 v[156:159], v[16:17], off offset:2048
	global_load_dwordx4 v[160:163], v[42:43], off
	global_load_dwordx4 v[164:167], v[12:13], off offset:3072
	global_load_dwordx4 v[168:171], v[14:15], off offset:3072
	global_load_dwordx4 v[172:175], v[24:25], off offset:3072
	global_load_dwordx4 v[176:179], v[26:27], off offset:3072
	global_load_dwordx4 v[180:183], v[16:17], off offset:3072
	global_load_dwordx4 v[184:187], v[44:45], off
	v_pk_add_f32 v[4:5], v[4:5], v[100:101]
	v_add_co_u32_e32 v32, vcc, s67, v18
	s_waitcnt vmcnt(20)
	v_pk_add_f32 v[8:9], v[6:7], v[106:107]
	v_pk_add_f32 v[10:11], v[4:5], v[104:105]
	v_addc_co_u32_e32 v33, vcc, 0, v19, vcc
	global_load_dwordx4 v[188:191], v[32:33], off
	v_add_co_u32_e32 v34, vcc, s68, v18
	s_waitcnt vmcnt(19)
	v_pk_fma_f32 v[2:3], v[8:9], v[114:115], v[110:111]
	v_pk_fma_f32 v[0:1], v[10:11], v[112:113], v[108:109]
	v_addc_co_u32_e32 v35, vcc, 0, v19, vcc
	global_load_dwordx4 v[192:195], v[34:35], off
	v_add_co_u32_e32 v82, vcc, s69, v18
	s_waitcnt vmcnt(18)
	v_pk_add_f32 v[10:11], v[118:119], v[122:123]
	v_pk_add_f32 v[8:9], v[116:117], v[120:121]
	v_addc_co_u32_e32 v83, vcc, 0, v19, vcc
	global_load_dwordx4 v[196:199], v[82:83], off
	v_add_co_u32_e32 v84, vcc, s70, v18
	s_waitcnt vmcnt(18)
	v_pk_add_f32 v[10:11], v[10:11], v[126:127]
	v_pk_add_f32 v[8:9], v[8:9], v[124:125]
	v_addc_co_u32_e32 v85, vcc, 0, v19, vcc
	global_load_dwordx4 v[200:203], v[84:85], off
	v_add_co_u32_e32 v86, vcc, s66, v16
	s_waitcnt vmcnt(18)
	v_pk_add_f32 v[20:21], v[10:11], v[130:131]
	v_pk_add_f32 v[22:23], v[8:9], v[128:129]
	v_addc_co_u32_e32 v87, vcc, 0, v17, vcc
	global_load_dwordx4 v[204:207], v[86:87], off
	global_load_dwordx4 v[210:213], v[46:47], off
	global_load_dwordx4 v[214:217], v[32:33], off offset:1024
	global_load_dwordx4 v[218:221], v[34:35], off offset:1024
	global_load_dwordx4 v[222:225], v[82:83], off offset:1024
	global_load_dwordx4 v[226:229], v[84:85], off offset:1024
	global_load_dwordx4 v[230:233], v[86:87], off offset:1024
	global_load_dwordx4 v[234:237], v[48:49], off
	global_load_dwordx4 v[238:241], v[32:33], off offset:2048
	global_load_dwordx4 v[242:245], v[34:35], off offset:2048
	global_load_dwordx4 v[246:249], v[82:83], off offset:2048
	global_load_dwordx4 v[92:95], v[84:85], off offset:2048
	global_load_dwordx4 v[96:99], v[86:87], off offset:2048
	global_load_dwordx4 v[100:103], v[50:51], off
	global_load_dwordx4 v[104:107], v[32:33], off offset:3072
	global_load_dwordx4 v[108:111], v[34:35], off offset:3072
	global_load_dwordx4 v[112:115], v[82:83], off offset:3072
	global_load_dwordx4 v[116:119], v[84:85], off offset:3072
	global_load_dwordx4 v[120:123], v[86:87], off offset:3072
	global_load_dwordx4 v[124:127], v[52:53], off
	s_waitcnt vmcnt(36)
	v_pk_fma_f32 v[10:11], v[20:21], v[138:139], v[134:135]
	v_pk_fma_f32 v[8:9], v[22:23], v[136:137], v[132:133]
	s_waitcnt vmcnt(34)
	v_pk_add_f32 v[22:23], v[142:143], v[146:147]
	v_pk_add_f32 v[20:21], v[140:141], v[144:145]
	s_waitcnt vmcnt(33)
	v_pk_add_f32 v[22:23], v[22:23], v[150:151]
	v_pk_add_f32 v[20:21], v[20:21], v[148:149]
	s_waitcnt vmcnt(32)
	v_pk_add_f32 v[28:29], v[22:23], v[154:155]
	v_pk_add_f32 v[30:31], v[20:21], v[152:153]
	s_waitcnt vmcnt(30)
	v_pk_fma_f32 v[6:7], v[28:29], v[162:163], v[158:159]
	v_pk_fma_f32 v[4:5], v[30:31], v[160:161], v[156:157]
	s_nop 0
	s_waitcnt vmcnt(28)
	v_pk_add_f32 v[22:23], v[166:167], v[170:171]
	v_pk_add_f32 v[20:21], v[164:165], v[168:169]
	s_waitcnt vmcnt(27)
	v_pk_add_f32 v[22:23], v[22:23], v[174:175]
	v_pk_add_f32 v[20:21], v[20:21], v[172:173]
	s_waitcnt vmcnt(26)
	v_pk_add_f32 v[24:25], v[22:23], v[178:179]
	v_pk_add_f32 v[26:27], v[20:21], v[176:177]
	s_waitcnt vmcnt(24)
	v_pk_fma_f32 v[14:15], v[24:25], v[186:187], v[182:183]
	v_pk_fma_f32 v[12:13], v[26:27], v[184:185], v[180:181]
	s_waitcnt vmcnt(22)
	v_pk_add_f32 v[26:27], v[190:191], v[194:195]
	v_pk_add_f32 v[24:25], v[188:189], v[192:193]
	s_waitcnt vmcnt(21)
; __device__ __forceinline__ int lane_fresh() { int l; asm volatile("v_mbcnt_lo_u32_b32 %0, -1, 0\n\tv_mbcnt_hi_u32_b32 %0, -1, %0" : "=v"(l)); return l; }
;     __device__ __forceinline__ unsigned char* ws() const { return (unsigned char*)(__attribute__((address_space(1))) unsigned char*)get(35); }
; template <int M> __device__ __forceinline__ float shx(float v) {
;     if constexpr (M < 32) return __builtin_bit_cast(float, __builtin_amdgcn_ds_swizzle(__builtin_bit_cast(int, v), (M << 10) | 0x1f));
;     else return __builtin_bit_cast(float, __builtin_amdgcn_ds_bpermute((lane_fresh() ^ 32) << 2, __builtin_bit_cast(int, v)));
; }
; __device__ __forceinline__ float wave_sum(float v) { v += shx<1>(v); v += shx<2>(v); v += shx<4>(v); v += shx<8>(v); v += shx<16>(v); v += shx<32>(v); return v; }
; __device__ __forceinline__ void outproj_ctx_rows(const PA& a, int layer, int gw, int NGW, int lane) {
;     ...
;         const f32x4* xs = (const f32x4*)(srcb + (size_t)rc * D) + lane; f32x4* xr = (f32x4*)(a.ws() + WS_XC + (size_t)rc * D * 4) + lane; f32x4 v[8]; float ss = 0.f;
; #pragma unroll
;         for (int j = 0; j < 8; ++j) { const int col = (lane + 64 * j) * 4; const float* pp = part + (size_t)rc * D + col;
;             const f32x4 p = ((*(const f32x4*)pp + *(const f32x4*)(pp + (size_t)NCTX * D)) + *(const f32x4*)(pp + (size_t)2 * NCTX * D)) + *(const f32x4*)(pp + (size_t)3 * NCTX * D);
;             v[j] = xs[64 * j] + *(const f32x4*)(mv + 2 * D + col) * p; }
; #pragma unroll
;         for (int j = 0; j < 8; ++j) { xr[64 * j] = v[j]; ss += (v[j].x * v[j].x + v[j].y * v[j].y) + (v[j].z * v[j].z + v[j].w * v[j].w); }
;         const float sm = wave_sum(ss); if (lane == 0) ((float*)(a.ws() + WS_RS2))[NLAT + rc] = 1.f / sqrtf(sm * (1.f / D) + EPS);
	v_pk_add_f32 v[24:25], v[24:25], v[196:197]
	v_pk_add_f32 v[22:23], v[26:27], v[198:199]
	s_waitcnt vmcnt(20)
	v_pk_add_f32 v[24:25], v[24:25], v[200:201]
	v_pk_add_f32 v[26:27], v[22:23], v[202:203]
	s_waitcnt vmcnt(18)
	v_pk_fma_f32 v[18:19], v[26:27], v[212:213], v[206:207]
	v_pk_fma_f32 v[16:17], v[24:25], v[210:211], v[204:205]
	s_waitcnt vmcnt(16)
	v_pk_add_f32 v[26:27], v[216:217], v[220:221]
	v_pk_add_f32 v[24:25], v[214:215], v[218:219]
	s_waitcnt vmcnt(15)
	v_pk_add_f32 v[26:27], v[26:27], v[224:225]
	v_pk_add_f32 v[24:25], v[24:25], v[222:223]
	s_waitcnt vmcnt(14)
	v_pk_add_f32 v[28:29], v[26:27], v[228:229]
	v_pk_add_f32 v[30:31], v[24:25], v[226:227]
	s_waitcnt vmcnt(12)
	v_pk_fma_f32 v[22:23], v[28:29], v[236:237], v[232:233]
	v_pk_fma_f32 v[20:21], v[30:31], v[234:235], v[230:231]
	s_waitcnt vmcnt(10)
	v_pk_add_f32 v[30:31], v[240:241], v[244:245]
	v_pk_add_f32 v[28:29], v[238:239], v[242:243]
	s_waitcnt vmcnt(9)
	v_pk_add_f32 v[30:31], v[30:31], v[248:249]
	v_pk_add_f32 v[28:29], v[28:29], v[246:247]
	s_waitcnt vmcnt(8)
	v_pk_add_f32 v[88:89], v[30:31], v[94:95]
	v_pk_add_f32 v[90:91], v[28:29], v[92:93]
	s_waitcnt vmcnt(6)
	v_pk_fma_f32 v[26:27], v[88:89], v[102:103], v[98:99]
	v_pk_fma_f32 v[24:25], v[90:91], v[100:101], v[96:97]
	s_nop 0
	s_waitcnt vmcnt(4)
	v_pk_add_f32 v[34:35], v[106:107], v[110:111]
	v_pk_add_f32 v[32:33], v[104:105], v[108:109]
	s_waitcnt vmcnt(3)
	v_pk_add_f32 v[34:35], v[34:35], v[114:115]
	v_pk_add_f32 v[32:33], v[32:33], v[112:113]
	s_waitcnt vmcnt(2)
	v_pk_add_f32 v[82:83], v[34:35], v[118:119]
	v_pk_add_f32 v[84:85], v[32:33], v[116:117]
	s_waitcnt vmcnt(0)
	v_pk_fma_f32 v[30:31], v[82:83], v[126:127], v[122:123]
	v_mul_f32_e32 v82, v1, v1
	v_mul_f32_e32 v83, v3, v3
	v_fmac_f32_e32 v82, v0, v0
	v_fmac_f32_e32 v83, v2, v2
	v_pk_fma_f32 v[28:29], v[84:85], v[124:125], v[120:121]
	v_add_f32_e32 v82, v82, v83
	v_mul_f32_e32 v83, v9, v9
	v_mul_f32_e32 v84, v11, v11
	v_lshl_add_u64 v[32:33], s[6:7], 0, v[80:81]
	s_mov_b32 s6, 0xbe00000
	v_fmac_f32_e32 v83, v8, v8
	v_fmac_f32_e32 v84, v10, v10
	v_add_co_u32_e32 v34, vcc, s6, v32
	v_add_f32_e32 v83, v83, v84
	s_nop 0
	v_addc_co_u32_e32 v35, vcc, 0, v33, vcc
	v_add_f32_e32 v82, v82, v83
	v_mul_f32_e32 v83, v5, v5
	v_mul_f32_e32 v84, v7, v7
	global_store_dwordx4 v[34:35], v[8:11], off offset:1024
	global_store_dwordx4 v[34:35], v[4:7], off offset:2048
	v_fmac_f32_e32 v83, v4, v4
	v_fmac_f32_e32 v84, v6, v6
	global_store_dwordx4 v[34:35], v[12:15], off offset:3072
	v_mul_f32_e32 v34, v13, v13
	v_mul_f32_e32 v35, v15, v15
	v_add_f32_e32 v83, v83, v84
	v_fmac_f32_e32 v34, v12, v12
	v_fmac_f32_e32 v35, v14, v14
	v_add_f32_e32 v82, v82, v83
	v_add_f32_e32 v34, v34, v35
	v_add_f32_e32 v34, v82, v34
	v_mul_f32_e32 v35, v17, v17
	v_mul_f32_e32 v82, v19, v19
	v_fmac_f32_e32 v35, v16, v16
	v_fmac_f32_e32 v82, v18, v18
	v_add_f32_e32 v35, v35, v82
	v_add_f32_e32 v34, v34, v35
	v_mul_f32_e32 v35, v21, v21
	v_mul_f32_e32 v82, v23, v23
	s_mov_b32 s6, 0xbe01000
	v_fmac_f32_e32 v35, v20, v20
	v_fmac_f32_e32 v82, v22, v22
	v_add_co_u32_e32 v32, vcc, s6, v32
	v_add_f32_e32 v35, v35, v82
	s_nop 0
	v_addc_co_u32_e32 v33, vcc, 0, v33, vcc
	v_add_f32_e32 v34, v34, v35
	v_mul_f32_e32 v35, v25, v25
	v_mul_f32_e32 v82, v27, v27
	global_store_dwordx4 v[32:33], v[0:3], off offset:-4096
	global_store_dwordx4 v[32:33], v[16:19], off
	global_store_dwordx4 v[32:33], v[20:23], off offset:1024
	global_store_dwordx4 v[32:33], v[24:27], off offset:2048
	v_fmac_f32_e32 v35, v24, v24
	v_fmac_f32_e32 v82, v26, v26
	global_store_dwordx4 v[32:33], v[28:31], off offset:3072
	v_mul_f32_e32 v32, v29, v29
	v_mul_f32_e32 v33, v31, v31
	v_add_f32_e32 v35, v35, v82
	v_fmac_f32_e32 v32, v28, v28
	v_fmac_f32_e32 v33, v30, v30
	v_add_f32_e32 v34, v34, v35
	v_add_f32_e32 v32, v32, v33
	v_add_f32_e32 v32, v34, v32
	ds_swizzle_b32 v33, v32 offset:swizzle(SWAP,1)
	s_waitcnt lgkmcnt(0)
	v_add_f32_e32 v32, v32, v33
	ds_swizzle_b32 v33, v32 offset:swizzle(SWAP,2)
	s_waitcnt lgkmcnt(0)
	v_add_f32_e32 v32, v32, v33
	ds_swizzle_b32 v33, v32 offset:swizzle(SWAP,4)
	s_waitcnt lgkmcnt(0)
	v_add_f32_e32 v32, v32, v33
	ds_swizzle_b32 v33, v32 offset:swizzle(SWAP,8)
	s_waitcnt lgkmcnt(0)
	v_add_f32_e32 v32, v32, v33
	ds_swizzle_b32 v33, v32 offset:swizzle(SWAP,16)
	s_waitcnt lgkmcnt(0)
	v_add_f32_e32 v32, v32, v33
	v_mbcnt_lo_u32_b32 v33, -1, 0
	v_mbcnt_hi_u32_b32 v33, -1, v33
	s_nop 0
	v_lshlrev_b32_e32 v33, 2, v33
	v_xor_b32_e32 v33, 0x80, v33
	ds_bpermute_b32 v33, v33, v32
	s_and_saveexec_b64 s[22:23], s[0:1]
	s_cbranch_execz .LBB0_1414
	s_waitcnt lgkmcnt(0)
	v_add_f32_e32 v32, v32, v33
	v_fmamk_f32 v32, v32, 0x3a000000, v250
	v_cmp_gt_f32_e32 vcc, s97, v32
	v_mul_f32_e32 v33, 0x4f800000, v32
	s_nop 0
	v_cndmask_b32_e32 v32, v32, v33, vcc
	v_sqrt_f32_e32 v33, v32
	s_nop 0
	v_add_u32_e32 v34, -1, v33
	v_fma_f32 v35, -v34, v33, v32
	v_cmp_ge_f32_e64 s[6:7], 0, v35
	v_add_u32_e32 v35, 1, v33
	s_nop 0
	v_cndmask_b32_e64 v34, v33, v34, s[6:7]
	v_fma_f32 v33, -v35, v33, v32
	v_cmp_lt_f32_e64 s[6:7], 0, v33
	s_nop 1
	v_cndmask_b32_e64 v33, v34, v35, s[6:7]
	v_mul_f32_e32 v34, 0x37800000, v33
	v_cndmask_b32_e32 v33, v33, v34, vcc
	v_cmp_class_f32_e32 vcc, v32, v251
	s_nop 1
	v_cndmask_b32_e32 v32, v33, v32, vcc
	v_div_scale_f32 v33, s[6:7], v32, v32, 1.0
	v_rcp_f32_e32 v34, v33
	s_nop 0
	v_fma_f32 v35, -v33, v34, 1.0
	v_fmac_f32_e32 v34, v35, v34
	v_div_scale_f32 v35, vcc, 1.0, v32, 1.0
	v_mul_f32_e32 v82, v35, v34
	v_fma_f32 v83, -v33, v82, v35
	v_fmac_f32_e32 v82, v83, v34
	v_fma_f32 v33, -v33, v82, v35
	v_div_fmas_f32 v33, v33, v34, v82
	v_div_fixup_f32 v32, v33, v32, 1.0
	v_mov_b32 v33, 0
	s_nop 0
	v_add_u32_e32 v33, s79, v33
	ds_read_b32 v34, v33 offset:280
	ds_read_b32 v33, v33 offset:284
	s_waitcnt lgkmcnt(1)
	v_readfirstlane_b32 s6, v34
	s_waitcnt lgkmcnt(0)
	v_readfirstlane_b32 s7, v33
	s_add_u32 s6, s6, s24
	s_addc_u32 s7, s7, s25
	s_nop 2
	global_store_dword v209, v32, s[6:7]
	s_branch .LBB0_1414
